# hand-written pool phase (one wave per 16-row x group task, single load round trip, sliding window) + XCD-local barrier pool->pool GEMM
# speedup vs baseline: 1.0529x; 1.0135x over previous
.LBB0_242:
	v_readlane_b32 s2, v255, 14
	v_readlane_b32 s3, v255, 15
	s_mov_b64 s[40:41], s[88:89]
	s_waitcnt vmcnt(0)
	v_mov_b32_e32 v0, v204
	s_andn2_b64 vcc, exec, s[2:3]
	s_cbranch_vccnz .LBB0_319
	s_load_dwordx2 s[80:81], s[40:41], 0xb8
	v_mov_b32_e32 v0, 0x2080c
	ds_read_b32 v0, v0
	v_readfirstlane_b32 s84, v204
	s_lshr_b32 s84, s84, 6
	s_and_b32 s82, s84, 3
	s_lshr_b32 s84, s84, 2
	s_waitcnt lgkmcnt(0)
	v_readfirstlane_b32 s85, v0
	s_and_b32 s100, s85, 7
	s_lshr_b32 s85, s85, 3
	s_mulk_i32 s100, 0x600
	s_lshl_b32 s85, s85, 1
	s_add_i32 s71, s85, s84
	v_lshlrev_b32_e32 v62, 3, v205
.Lpool_task:
	s_lshl_b32 s83, s71, 4
	s_add_i32 s83, s83, s100
	s_cmpk_lt_u32 s83, 0x1000
	s_mov_b32 s84, 0xfff
	s_cselect_b32 s84, 0xff, s84
	s_and_b32 s85, s83, s84
	s_cmp_eq_u32 s85, 0
	s_cselect_b32 s86, 1, 0
	s_add_i32 s85, s83, 16
	s_and_b32 s85, s85, s84
	s_cmp_eq_u32 s85, 0
	s_cselect_b32 s87, 1, 0
	s_cmp_eq_u32 s82, 0
	s_cbranch_scc1 .Lpool_g0
	s_cmp_eq_u32 s82, 1
	s_cbranch_scc1 .Lpool_g1
	s_cmp_eq_u32 s82, 2
	s_cbranch_scc1 .Lpool_g2
	s_branch .Lpool_g3
.Lpool_g0:
	s_sub_i32 s84, s83, 1
	v_add_u32_e32 v64, s84, v205
	s_cmp_lg_u32 s86, 0
	s_cselect_b32 s85, 1, 0
	s_cmp_lg_u32 s87, 0
	s_cselect_b32 s101, 17, 17
	v_cmp_le_u32_e64 s[4:5], s85, v205
	v_cmp_gt_u32_e32 vcc, s101, v205
	s_and_b64 vcc, vcc, s[4:5]
	v_mov_b32_e32 v65, s83
	v_cndmask_b32_e32 v64, v65, v64, vcc
	v_lshlrev_b32_e32 v64, 6, v64
	s_add_u32 s2, s80, 0x13648000
	s_addc_u32 s3, s81, 0
	global_load_dwordx4 v[66:69], v64, s[2:3]
	global_load_dwordx4 v[70:73], v64, s[2:3] offset:16
	global_load_dwordx4 v[74:77], v64, s[2:3] offset:32
	global_load_dwordx4 v[78:81], v64, s[2:3] offset:48
	s_add_u32 s2, s80, 0x87c8000
	s_addc_u32 s3, s81, 0
	s_lshl_b32 s85, s83, 11
	s_add_u32 s4, s2, s85
	s_addc_u32 s5, s3, 0
	s_sub_u32 s2, s4, 0x800
	s_subb_u32 s3, s5, 0
	s_cmp_lg_u32 s86, 0
	s_cselect_b64 s[84:85], s[4:5], s[2:3]
	global_load_dwordx2 v[0:1], v62, s[84:85]
	s_add_u32 s2, s2, 0x800
	s_addc_u32 s3, s3, 0
	global_load_dwordx2 v[2:3], v62, s[2:3]
	s_add_u32 s2, s2, 0x800
	s_addc_u32 s3, s3, 0
	global_load_dwordx2 v[4:5], v62, s[2:3]
	s_add_u32 s2, s2, 0x800
	s_addc_u32 s3, s3, 0
	global_load_dwordx2 v[6:7], v62, s[2:3]
	s_add_u32 s2, s2, 0x800
	s_addc_u32 s3, s3, 0
	global_load_dwordx2 v[8:9], v62, s[2:3]
	s_add_u32 s2, s2, 0x800
	s_addc_u32 s3, s3, 0
	global_load_dwordx2 v[10:11], v62, s[2:3]
	s_add_u32 s2, s2, 0x800
	s_addc_u32 s3, s3, 0
	global_load_dwordx2 v[12:13], v62, s[2:3]
	s_add_u32 s2, s2, 0x800
	s_addc_u32 s3, s3, 0
	global_load_dwordx2 v[14:15], v62, s[2:3]
	s_add_u32 s2, s2, 0x800
	s_addc_u32 s3, s3, 0
	global_load_dwordx2 v[16:17], v62, s[2:3]
	s_add_u32 s2, s2, 0x800
	s_addc_u32 s3, s3, 0
	global_load_dwordx2 v[18:19], v62, s[2:3]
	s_add_u32 s2, s2, 0x800
	s_addc_u32 s3, s3, 0
	global_load_dwordx2 v[20:21], v62, s[2:3]
	s_add_u32 s2, s2, 0x800
	s_addc_u32 s3, s3, 0
	global_load_dwordx2 v[22:23], v62, s[2:3]
	s_add_u32 s2, s2, 0x800
	s_addc_u32 s3, s3, 0
	global_load_dwordx2 v[24:25], v62, s[2:3]
	s_add_u32 s2, s2, 0x800
	s_addc_u32 s3, s3, 0
	global_load_dwordx2 v[26:27], v62, s[2:3]
	s_add_u32 s2, s2, 0x800
	s_addc_u32 s3, s3, 0
	global_load_dwordx2 v[28:29], v62, s[2:3]
	s_add_u32 s2, s2, 0x800
	s_addc_u32 s3, s3, 0
	global_load_dwordx2 v[30:31], v62, s[2:3]
	s_add_u32 s2, s2, 0x800
	s_addc_u32 s3, s3, 0
	global_load_dwordx2 v[32:33], v62, s[2:3]
	s_waitcnt vmcnt(17)
	v_add_f32_e32 v66, v66, v67
	v_add_f32_e32 v68, v68, v69
	v_add_f32_e32 v70, v70, v71
	v_add_f32_e32 v72, v72, v73
	v_add_f32_e32 v74, v74, v75
	v_add_f32_e32 v76, v76, v77
	v_add_f32_e32 v78, v78, v79
	v_add_f32_e32 v80, v80, v81
	v_add_f32_e32 v66, v66, v68
	v_add_f32_e32 v70, v70, v72
	v_add_f32_e32 v74, v74, v76
	v_add_f32_e32 v78, v78, v80
	v_add_f32_e32 v66, v66, v70
	v_add_f32_e32 v74, v74, v78
	v_add_f32_e32 v66, v66, v74
	v_fmamk_f32 v66, v66, 0x3a800000, v207
	v_rsq_f32_e32 v66, v66
	s_nop 0
	v_cndmask_b32_e32 v63, 0, v66, vcc
	s_nop 1
	v_readlane_b32 s40, v63, 0
	v_readlane_b32 s41, v63, 1
	v_readlane_b32 s42, v63, 2
	v_readlane_b32 s43, v63, 3
	v_readlane_b32 s44, v63, 4
	v_readlane_b32 s45, v63, 5
	v_readlane_b32 s46, v63, 6
	v_readlane_b32 s47, v63, 7
	v_readlane_b32 s48, v63, 8
	v_readlane_b32 s49, v63, 9
	v_readlane_b32 s50, v63, 10
	v_readlane_b32 s51, v63, 11
	v_readlane_b32 s52, v63, 12
	v_readlane_b32 s53, v63, 13
	v_readlane_b32 s54, v63, 14
	v_readlane_b32 s55, v63, 15
	v_readlane_b32 s56, v63, 16
	s_add_u32 s2, s80, 0x9fc8000
	s_addc_u32 s3, s81, 0
	s_lshl_b32 s85, s83, 11
	s_add_u32 s2, s2, s85
	s_addc_u32 s3, s3, 0
	s_waitcnt vmcnt(15)
	v_lshlrev_b32_e32 v86, 16, v0
	v_and_b32_e32 v87, 0xffff0000, v0
	v_lshlrev_b32_e32 v88, 16, v1
	v_and_b32_e32 v89, 0xffff0000, v1
	v_mul_f32_e32 v82, s40, v86
	v_mul_f32_e32 v83, s40, v87
	v_mul_f32_e32 v84, s40, v88
	v_mul_f32_e32 v85, s40, v89
	v_lshlrev_b32_e32 v86, 16, v2
	v_and_b32_e32 v87, 0xffff0000, v2
	v_lshlrev_b32_e32 v88, 16, v3
	v_and_b32_e32 v89, 0xffff0000, v3
	v_fmac_f32_e32 v82, s41, v86
	v_fmac_f32_e32 v83, s41, v87
	v_fmac_f32_e32 v84, s41, v88
	v_fmac_f32_e32 v85, s41, v89
	s_cmp_lg_u32 s86, 0
	s_mov_b32 s84, 0x3f000000
	s_cselect_b32 s84, 0x3f800000, s84
	v_lshlrev_b32_e32 v86, 16, v2
	v_and_b32_e32 v87, 0xffff0000, v2
	v_lshlrev_b32_e32 v88, 16, v3
	v_and_b32_e32 v89, 0xffff0000, v3
	v_mul_f32_e32 v86, s41, v86
	v_mul_f32_e32 v87, s41, v87
	v_mul_f32_e32 v88, s41, v88
	v_mul_f32_e32 v89, s41, v89
	v_fma_f32 v90, v82, s84, -v86
	v_fma_f32 v91, v83, s84, -v87
	v_fma_f32 v92, v84, s84, -v88
	v_fma_f32 v93, v85, s84, -v89
	v_cvt_pk_bf16_f32 v94, v90, v91
	v_cvt_pk_bf16_f32 v95, v92, v93
	global_store_dwordx2 v62, v[94:95], s[2:3]
	s_add_u32 s2, s2, 0x800
	s_addc_u32 s3, s3, 0
	s_waitcnt vmcnt(15)
	v_lshlrev_b32_e32 v86, 16, v4
	v_and_b32_e32 v87, 0xffff0000, v4
	v_lshlrev_b32_e32 v88, 16, v5
	v_and_b32_e32 v89, 0xffff0000, v5
	v_fmac_f32_e32 v82, s42, v86
	v_fmac_f32_e32 v83, s42, v87
	v_fmac_f32_e32 v84, s42, v88
	v_fmac_f32_e32 v85, s42, v89
	v_lshlrev_b32_e32 v86, 16, v0
	v_and_b32_e32 v87, 0xffff0000, v0
	v_lshlrev_b32_e32 v88, 16, v1
	v_and_b32_e32 v89, 0xffff0000, v1
	v_fma_f32 v82, -v86, s40, v82
	v_fma_f32 v83, -v87, s40, v83
	v_fma_f32 v84, -v88, s40, v84
	v_fma_f32 v85, -v89, s40, v85
	s_mov_b32 s84, 0x3f000000
	v_lshlrev_b32_e32 v86, 16, v4
	v_and_b32_e32 v87, 0xffff0000, v4
	v_lshlrev_b32_e32 v88, 16, v5
	v_and_b32_e32 v89, 0xffff0000, v5
	v_mul_f32_e32 v86, s42, v86
	v_mul_f32_e32 v87, s42, v87
	v_mul_f32_e32 v88, s42, v88
	v_mul_f32_e32 v89, s42, v89
	v_fma_f32 v90, v82, s84, -v86
	v_fma_f32 v91, v83, s84, -v87
	v_fma_f32 v92, v84, s84, -v88
	v_fma_f32 v93, v85, s84, -v89
	v_cvt_pk_bf16_f32 v94, v90, v91
	v_cvt_pk_bf16_f32 v95, v92, v93
	global_store_dwordx2 v62, v[94:95], s[2:3]
	s_add_u32 s2, s2, 0x800
	s_addc_u32 s3, s3, 0
	s_waitcnt vmcnt(15)
	v_lshlrev_b32_e32 v86, 16, v6
	v_and_b32_e32 v87, 0xffff0000, v6
	v_lshlrev_b32_e32 v88, 16, v7
	v_and_b32_e32 v89, 0xffff0000, v7
	v_fmac_f32_e32 v82, s43, v86
	v_fmac_f32_e32 v83, s43, v87
	v_fmac_f32_e32 v84, s43, v88
	v_fmac_f32_e32 v85, s43, v89
	v_lshlrev_b32_e32 v86, 16, v2
	v_and_b32_e32 v87, 0xffff0000, v2
	v_lshlrev_b32_e32 v88, 16, v3
	v_and_b32_e32 v89, 0xffff0000, v3
	v_fma_f32 v82, -v86, s41, v82
	v_fma_f32 v83, -v87, s41, v83
	v_fma_f32 v84, -v88, s41, v84
	v_fma_f32 v85, -v89, s41, v85
	s_mov_b32 s84, 0x3f000000
	v_lshlrev_b32_e32 v86, 16, v6
	v_and_b32_e32 v87, 0xffff0000, v6
	v_lshlrev_b32_e32 v88, 16, v7
	v_and_b32_e32 v89, 0xffff0000, v7
	v_mul_f32_e32 v86, s43, v86
	v_mul_f32_e32 v87, s43, v87
	v_mul_f32_e32 v88, s43, v88
	v_mul_f32_e32 v89, s43, v89
	v_fma_f32 v90, v82, s84, -v86
	v_fma_f32 v91, v83, s84, -v87
	v_fma_f32 v92, v84, s84, -v88
	v_fma_f32 v93, v85, s84, -v89
	v_cvt_pk_bf16_f32 v94, v90, v91
	v_cvt_pk_bf16_f32 v95, v92, v93
	global_store_dwordx2 v62, v[94:95], s[2:3]
	s_add_u32 s2, s2, 0x800
	s_addc_u32 s3, s3, 0
	s_waitcnt vmcnt(15)
	v_lshlrev_b32_e32 v86, 16, v8
	v_and_b32_e32 v87, 0xffff0000, v8
	v_lshlrev_b32_e32 v88, 16, v9
	v_and_b32_e32 v89, 0xffff0000, v9
	v_fmac_f32_e32 v82, s44, v86
	v_fmac_f32_e32 v83, s44, v87
	v_fmac_f32_e32 v84, s44, v88
	v_fmac_f32_e32 v85, s44, v89
	v_lshlrev_b32_e32 v86, 16, v4
	v_and_b32_e32 v87, 0xffff0000, v4
	v_lshlrev_b32_e32 v88, 16, v5
	v_and_b32_e32 v89, 0xffff0000, v5
	v_fma_f32 v82, -v86, s42, v82
	v_fma_f32 v83, -v87, s42, v83
	v_fma_f32 v84, -v88, s42, v84
	v_fma_f32 v85, -v89, s42, v85
	s_mov_b32 s84, 0x3f000000
	v_lshlrev_b32_e32 v86, 16, v8
	v_and_b32_e32 v87, 0xffff0000, v8
	v_lshlrev_b32_e32 v88, 16, v9
	v_and_b32_e32 v89, 0xffff0000, v9
	v_mul_f32_e32 v86, s44, v86
	v_mul_f32_e32 v87, s44, v87
	v_mul_f32_e32 v88, s44, v88
	v_mul_f32_e32 v89, s44, v89
	v_fma_f32 v90, v82, s84, -v86
	v_fma_f32 v91, v83, s84, -v87
	v_fma_f32 v92, v84, s84, -v88
	v_fma_f32 v93, v85, s84, -v89
	v_cvt_pk_bf16_f32 v94, v90, v91
	v_cvt_pk_bf16_f32 v95, v92, v93
	global_store_dwordx2 v62, v[94:95], s[2:3]
	s_add_u32 s2, s2, 0x800
	s_addc_u32 s3, s3, 0
	s_waitcnt vmcnt(15)
	v_lshlrev_b32_e32 v86, 16, v10
	v_and_b32_e32 v87, 0xffff0000, v10
	v_lshlrev_b32_e32 v88, 16, v11
	v_and_b32_e32 v89, 0xffff0000, v11
	v_fmac_f32_e32 v82, s45, v86
	v_fmac_f32_e32 v83, s45, v87
	v_fmac_f32_e32 v84, s45, v88
	v_fmac_f32_e32 v85, s45, v89
	v_lshlrev_b32_e32 v86, 16, v6
	v_and_b32_e32 v87, 0xffff0000, v6
	v_lshlrev_b32_e32 v88, 16, v7
	v_and_b32_e32 v89, 0xffff0000, v7
	v_fma_f32 v82, -v86, s43, v82
	v_fma_f32 v83, -v87, s43, v83
	v_fma_f32 v84, -v88, s43, v84
	v_fma_f32 v85, -v89, s43, v85
	s_mov_b32 s84, 0x3f000000
	v_lshlrev_b32_e32 v86, 16, v10
	v_and_b32_e32 v87, 0xffff0000, v10
	v_lshlrev_b32_e32 v88, 16, v11
	v_and_b32_e32 v89, 0xffff0000, v11
	v_mul_f32_e32 v86, s45, v86
	v_mul_f32_e32 v87, s45, v87
	v_mul_f32_e32 v88, s45, v88
	v_mul_f32_e32 v89, s45, v89
	v_fma_f32 v90, v82, s84, -v86
	v_fma_f32 v91, v83, s84, -v87
	v_fma_f32 v92, v84, s84, -v88
	v_fma_f32 v93, v85, s84, -v89
	v_cvt_pk_bf16_f32 v94, v90, v91
	v_cvt_pk_bf16_f32 v95, v92, v93
	global_store_dwordx2 v62, v[94:95], s[2:3]
	s_add_u32 s2, s2, 0x800
	s_addc_u32 s3, s3, 0
	s_waitcnt vmcnt(15)
	v_lshlrev_b32_e32 v86, 16, v12
	v_and_b32_e32 v87, 0xffff0000, v12
	v_lshlrev_b32_e32 v88, 16, v13
	v_and_b32_e32 v89, 0xffff0000, v13
	v_fmac_f32_e32 v82, s46, v86
	v_fmac_f32_e32 v83, s46, v87
	v_fmac_f32_e32 v84, s46, v88
	v_fmac_f32_e32 v85, s46, v89
	v_lshlrev_b32_e32 v86, 16, v8
	v_and_b32_e32 v87, 0xffff0000, v8
	v_lshlrev_b32_e32 v88, 16, v9
	v_and_b32_e32 v89, 0xffff0000, v9
	v_fma_f32 v82, -v86, s44, v82
	v_fma_f32 v83, -v87, s44, v83
	v_fma_f32 v84, -v88, s44, v84
	v_fma_f32 v85, -v89, s44, v85
	s_mov_b32 s84, 0x3f000000
	v_lshlrev_b32_e32 v86, 16, v12
	v_and_b32_e32 v87, 0xffff0000, v12
	v_lshlrev_b32_e32 v88, 16, v13
	v_and_b32_e32 v89, 0xffff0000, v13
	v_mul_f32_e32 v86, s46, v86
	v_mul_f32_e32 v87, s46, v87
	v_mul_f32_e32 v88, s46, v88
	v_mul_f32_e32 v89, s46, v89
	v_fma_f32 v90, v82, s84, -v86
	v_fma_f32 v91, v83, s84, -v87
	v_fma_f32 v92, v84, s84, -v88
	v_fma_f32 v93, v85, s84, -v89
	v_cvt_pk_bf16_f32 v94, v90, v91
	v_cvt_pk_bf16_f32 v95, v92, v93
	global_store_dwordx2 v62, v[94:95], s[2:3]
	s_add_u32 s2, s2, 0x800
	s_addc_u32 s3, s3, 0
	s_waitcnt vmcnt(15)
	v_lshlrev_b32_e32 v86, 16, v14
	v_and_b32_e32 v87, 0xffff0000, v14
	v_lshlrev_b32_e32 v88, 16, v15
	v_and_b32_e32 v89, 0xffff0000, v15
	v_fmac_f32_e32 v82, s47, v86
	v_fmac_f32_e32 v83, s47, v87
	v_fmac_f32_e32 v84, s47, v88
	v_fmac_f32_e32 v85, s47, v89
	v_lshlrev_b32_e32 v86, 16, v10
	v_and_b32_e32 v87, 0xffff0000, v10
	v_lshlrev_b32_e32 v88, 16, v11
	v_and_b32_e32 v89, 0xffff0000, v11
	v_fma_f32 v82, -v86, s45, v82
	v_fma_f32 v83, -v87, s45, v83
	v_fma_f32 v84, -v88, s45, v84
	v_fma_f32 v85, -v89, s45, v85
	s_mov_b32 s84, 0x3f000000
	v_lshlrev_b32_e32 v86, 16, v14
	v_and_b32_e32 v87, 0xffff0000, v14
	v_lshlrev_b32_e32 v88, 16, v15
	v_and_b32_e32 v89, 0xffff0000, v15
	v_mul_f32_e32 v86, s47, v86
	v_mul_f32_e32 v87, s47, v87
	v_mul_f32_e32 v88, s47, v88
	v_mul_f32_e32 v89, s47, v89
	v_fma_f32 v90, v82, s84, -v86
	v_fma_f32 v91, v83, s84, -v87
	v_fma_f32 v92, v84, s84, -v88
	v_fma_f32 v93, v85, s84, -v89
	v_cvt_pk_bf16_f32 v94, v90, v91
	v_cvt_pk_bf16_f32 v95, v92, v93
	global_store_dwordx2 v62, v[94:95], s[2:3]
	s_add_u32 s2, s2, 0x800
	s_addc_u32 s3, s3, 0
	s_waitcnt vmcnt(15)
	v_lshlrev_b32_e32 v86, 16, v16
	v_and_b32_e32 v87, 0xffff0000, v16
	v_lshlrev_b32_e32 v88, 16, v17
	v_and_b32_e32 v89, 0xffff0000, v17
	v_fmac_f32_e32 v82, s48, v86
	v_fmac_f32_e32 v83, s48, v87
	v_fmac_f32_e32 v84, s48, v88
	v_fmac_f32_e32 v85, s48, v89
	v_lshlrev_b32_e32 v86, 16, v12
	v_and_b32_e32 v87, 0xffff0000, v12
	v_lshlrev_b32_e32 v88, 16, v13
	v_and_b32_e32 v89, 0xffff0000, v13
	v_fma_f32 v82, -v86, s46, v82
	v_fma_f32 v83, -v87, s46, v83
	v_fma_f32 v84, -v88, s46, v84
	v_fma_f32 v85, -v89, s46, v85
	s_mov_b32 s84, 0x3f000000
	v_lshlrev_b32_e32 v86, 16, v16
	v_and_b32_e32 v87, 0xffff0000, v16
	v_lshlrev_b32_e32 v88, 16, v17
	v_and_b32_e32 v89, 0xffff0000, v17
	v_mul_f32_e32 v86, s48, v86
	v_mul_f32_e32 v87, s48, v87
	v_mul_f32_e32 v88, s48, v88
	v_mul_f32_e32 v89, s48, v89
	v_fma_f32 v90, v82, s84, -v86
	v_fma_f32 v91, v83, s84, -v87
	v_fma_f32 v92, v84, s84, -v88
	v_fma_f32 v93, v85, s84, -v89
	v_cvt_pk_bf16_f32 v94, v90, v91
	v_cvt_pk_bf16_f32 v95, v92, v93
	global_store_dwordx2 v62, v[94:95], s[2:3]
	s_add_u32 s2, s2, 0x800
	s_addc_u32 s3, s3, 0
	s_waitcnt vmcnt(15)
	v_lshlrev_b32_e32 v86, 16, v18
	v_and_b32_e32 v87, 0xffff0000, v18
	v_lshlrev_b32_e32 v88, 16, v19
	v_and_b32_e32 v89, 0xffff0000, v19
	v_fmac_f32_e32 v82, s49, v86
	v_fmac_f32_e32 v83, s49, v87
	v_fmac_f32_e32 v84, s49, v88
	v_fmac_f32_e32 v85, s49, v89
	v_lshlrev_b32_e32 v86, 16, v14
	v_and_b32_e32 v87, 0xffff0000, v14
	v_lshlrev_b32_e32 v88, 16, v15
	v_and_b32_e32 v89, 0xffff0000, v15
	v_fma_f32 v82, -v86, s47, v82
	v_fma_f32 v83, -v87, s47, v83
	v_fma_f32 v84, -v88, s47, v84
	v_fma_f32 v85, -v89, s47, v85
	s_mov_b32 s84, 0x3f000000
	v_lshlrev_b32_e32 v86, 16, v18
	v_and_b32_e32 v87, 0xffff0000, v18
	v_lshlrev_b32_e32 v88, 16, v19
	v_and_b32_e32 v89, 0xffff0000, v19
	v_mul_f32_e32 v86, s49, v86
	v_mul_f32_e32 v87, s49, v87
	v_mul_f32_e32 v88, s49, v88
	v_mul_f32_e32 v89, s49, v89
	v_fma_f32 v90, v82, s84, -v86
	v_fma_f32 v91, v83, s84, -v87
	v_fma_f32 v92, v84, s84, -v88
	v_fma_f32 v93, v85, s84, -v89
	v_cvt_pk_bf16_f32 v94, v90, v91
	v_cvt_pk_bf16_f32 v95, v92, v93
	global_store_dwordx2 v62, v[94:95], s[2:3]
	s_add_u32 s2, s2, 0x800
	s_addc_u32 s3, s3, 0
	s_waitcnt vmcnt(15)
	v_lshlrev_b32_e32 v86, 16, v20
	v_and_b32_e32 v87, 0xffff0000, v20
	v_lshlrev_b32_e32 v88, 16, v21
	v_and_b32_e32 v89, 0xffff0000, v21
	v_fmac_f32_e32 v82, s50, v86
	v_fmac_f32_e32 v83, s50, v87
	v_fmac_f32_e32 v84, s50, v88
	v_fmac_f32_e32 v85, s50, v89
	v_lshlrev_b32_e32 v86, 16, v16
	v_and_b32_e32 v87, 0xffff0000, v16
	v_lshlrev_b32_e32 v88, 16, v17
	v_and_b32_e32 v89, 0xffff0000, v17
	v_fma_f32 v82, -v86, s48, v82
	v_fma_f32 v83, -v87, s48, v83
	v_fma_f32 v84, -v88, s48, v84
	v_fma_f32 v85, -v89, s48, v85
	s_mov_b32 s84, 0x3f000000
	v_lshlrev_b32_e32 v86, 16, v20
	v_and_b32_e32 v87, 0xffff0000, v20
	v_lshlrev_b32_e32 v88, 16, v21
	v_and_b32_e32 v89, 0xffff0000, v21
	v_mul_f32_e32 v86, s50, v86
	v_mul_f32_e32 v87, s50, v87
	v_mul_f32_e32 v88, s50, v88
	v_mul_f32_e32 v89, s50, v89
	v_fma_f32 v90, v82, s84, -v86
	v_fma_f32 v91, v83, s84, -v87
	v_fma_f32 v92, v84, s84, -v88
	v_fma_f32 v93, v85, s84, -v89
	v_cvt_pk_bf16_f32 v94, v90, v91
	v_cvt_pk_bf16_f32 v95, v92, v93
	global_store_dwordx2 v62, v[94:95], s[2:3]
	s_add_u32 s2, s2, 0x800
	s_addc_u32 s3, s3, 0
	s_waitcnt vmcnt(15)
	v_lshlrev_b32_e32 v86, 16, v22
	v_and_b32_e32 v87, 0xffff0000, v22
	v_lshlrev_b32_e32 v88, 16, v23
	v_and_b32_e32 v89, 0xffff0000, v23
	v_fmac_f32_e32 v82, s51, v86
	v_fmac_f32_e32 v83, s51, v87
	v_fmac_f32_e32 v84, s51, v88
	v_fmac_f32_e32 v85, s51, v89
	v_lshlrev_b32_e32 v86, 16, v18
	v_and_b32_e32 v87, 0xffff0000, v18
	v_lshlrev_b32_e32 v88, 16, v19
	v_and_b32_e32 v89, 0xffff0000, v19
	v_fma_f32 v82, -v86, s49, v82
	v_fma_f32 v83, -v87, s49, v83
	v_fma_f32 v84, -v88, s49, v84
	v_fma_f32 v85, -v89, s49, v85
	s_mov_b32 s84, 0x3f000000
	v_lshlrev_b32_e32 v86, 16, v22
	v_and_b32_e32 v87, 0xffff0000, v22
	v_lshlrev_b32_e32 v88, 16, v23
	v_and_b32_e32 v89, 0xffff0000, v23
	v_mul_f32_e32 v86, s51, v86
	v_mul_f32_e32 v87, s51, v87
	v_mul_f32_e32 v88, s51, v88
	v_mul_f32_e32 v89, s51, v89
	v_fma_f32 v90, v82, s84, -v86
	v_fma_f32 v91, v83, s84, -v87
	v_fma_f32 v92, v84, s84, -v88
	v_fma_f32 v93, v85, s84, -v89
	v_cvt_pk_bf16_f32 v94, v90, v91
	v_cvt_pk_bf16_f32 v95, v92, v93
	global_store_dwordx2 v62, v[94:95], s[2:3]
	s_add_u32 s2, s2, 0x800
	s_addc_u32 s3, s3, 0
	s_waitcnt vmcnt(15)
	v_lshlrev_b32_e32 v86, 16, v24
	v_and_b32_e32 v87, 0xffff0000, v24
	v_lshlrev_b32_e32 v88, 16, v25
	v_and_b32_e32 v89, 0xffff0000, v25
	v_fmac_f32_e32 v82, s52, v86
	v_fmac_f32_e32 v83, s52, v87
	v_fmac_f32_e32 v84, s52, v88
	v_fmac_f32_e32 v85, s52, v89
	v_lshlrev_b32_e32 v86, 16, v20
	v_and_b32_e32 v87, 0xffff0000, v20
	v_lshlrev_b32_e32 v88, 16, v21
	v_and_b32_e32 v89, 0xffff0000, v21
	v_fma_f32 v82, -v86, s50, v82
	v_fma_f32 v83, -v87, s50, v83
	v_fma_f32 v84, -v88, s50, v84
	v_fma_f32 v85, -v89, s50, v85
	s_mov_b32 s84, 0x3f000000
	v_lshlrev_b32_e32 v86, 16, v24
	v_and_b32_e32 v87, 0xffff0000, v24
	v_lshlrev_b32_e32 v88, 16, v25
	v_and_b32_e32 v89, 0xffff0000, v25
	v_mul_f32_e32 v86, s52, v86
	v_mul_f32_e32 v87, s52, v87
	v_mul_f32_e32 v88, s52, v88
	v_mul_f32_e32 v89, s52, v89
	v_fma_f32 v90, v82, s84, -v86
	v_fma_f32 v91, v83, s84, -v87
	v_fma_f32 v92, v84, s84, -v88
	v_fma_f32 v93, v85, s84, -v89
	v_cvt_pk_bf16_f32 v94, v90, v91
	v_cvt_pk_bf16_f32 v95, v92, v93
	global_store_dwordx2 v62, v[94:95], s[2:3]
	s_add_u32 s2, s2, 0x800
	s_addc_u32 s3, s3, 0
	s_waitcnt vmcnt(15)
	v_lshlrev_b32_e32 v86, 16, v26
	v_and_b32_e32 v87, 0xffff0000, v26
	v_lshlrev_b32_e32 v88, 16, v27
	v_and_b32_e32 v89, 0xffff0000, v27
	v_fmac_f32_e32 v82, s53, v86
	v_fmac_f32_e32 v83, s53, v87
	v_fmac_f32_e32 v84, s53, v88
	v_fmac_f32_e32 v85, s53, v89
	v_lshlrev_b32_e32 v86, 16, v22
	v_and_b32_e32 v87, 0xffff0000, v22
	v_lshlrev_b32_e32 v88, 16, v23
	v_and_b32_e32 v89, 0xffff0000, v23
	v_fma_f32 v82, -v86, s51, v82
	v_fma_f32 v83, -v87, s51, v83
	v_fma_f32 v84, -v88, s51, v84
	v_fma_f32 v85, -v89, s51, v85
	s_mov_b32 s84, 0x3f000000
	v_lshlrev_b32_e32 v86, 16, v26
	v_and_b32_e32 v87, 0xffff0000, v26
	v_lshlrev_b32_e32 v88, 16, v27
	v_and_b32_e32 v89, 0xffff0000, v27
	v_mul_f32_e32 v86, s53, v86
	v_mul_f32_e32 v87, s53, v87
	v_mul_f32_e32 v88, s53, v88
	v_mul_f32_e32 v89, s53, v89
	v_fma_f32 v90, v82, s84, -v86
	v_fma_f32 v91, v83, s84, -v87
	v_fma_f32 v92, v84, s84, -v88
	v_fma_f32 v93, v85, s84, -v89
	v_cvt_pk_bf16_f32 v94, v90, v91
	v_cvt_pk_bf16_f32 v95, v92, v93
	global_store_dwordx2 v62, v[94:95], s[2:3]
	s_add_u32 s2, s2, 0x800
	s_addc_u32 s3, s3, 0
	s_waitcnt vmcnt(15)
	v_lshlrev_b32_e32 v86, 16, v28
	v_and_b32_e32 v87, 0xffff0000, v28
	v_lshlrev_b32_e32 v88, 16, v29
	v_and_b32_e32 v89, 0xffff0000, v29
	v_fmac_f32_e32 v82, s54, v86
	v_fmac_f32_e32 v83, s54, v87
	v_fmac_f32_e32 v84, s54, v88
	v_fmac_f32_e32 v85, s54, v89
	v_lshlrev_b32_e32 v86, 16, v24
	v_and_b32_e32 v87, 0xffff0000, v24
	v_lshlrev_b32_e32 v88, 16, v25
	v_and_b32_e32 v89, 0xffff0000, v25
	v_fma_f32 v82, -v86, s52, v82
	v_fma_f32 v83, -v87, s52, v83
	v_fma_f32 v84, -v88, s52, v84
	v_fma_f32 v85, -v89, s52, v85
	s_mov_b32 s84, 0x3f000000
	v_lshlrev_b32_e32 v86, 16, v28
	v_and_b32_e32 v87, 0xffff0000, v28
	v_lshlrev_b32_e32 v88, 16, v29
	v_and_b32_e32 v89, 0xffff0000, v29
	v_mul_f32_e32 v86, s54, v86
	v_mul_f32_e32 v87, s54, v87
	v_mul_f32_e32 v88, s54, v88
	v_mul_f32_e32 v89, s54, v89
	v_fma_f32 v90, v82, s84, -v86
	v_fma_f32 v91, v83, s84, -v87
	v_fma_f32 v92, v84, s84, -v88
	v_fma_f32 v93, v85, s84, -v89
	v_cvt_pk_bf16_f32 v94, v90, v91
	v_cvt_pk_bf16_f32 v95, v92, v93
	global_store_dwordx2 v62, v[94:95], s[2:3]
	s_add_u32 s2, s2, 0x800
	s_addc_u32 s3, s3, 0
	s_waitcnt vmcnt(15)
	v_lshlrev_b32_e32 v86, 16, v30
	v_and_b32_e32 v87, 0xffff0000, v30
	v_lshlrev_b32_e32 v88, 16, v31
	v_and_b32_e32 v89, 0xffff0000, v31
	v_fmac_f32_e32 v82, s55, v86
	v_fmac_f32_e32 v83, s55, v87
	v_fmac_f32_e32 v84, s55, v88
	v_fmac_f32_e32 v85, s55, v89
	v_lshlrev_b32_e32 v86, 16, v26
	v_and_b32_e32 v87, 0xffff0000, v26
	v_lshlrev_b32_e32 v88, 16, v27
	v_and_b32_e32 v89, 0xffff0000, v27
	v_fma_f32 v82, -v86, s53, v82
	v_fma_f32 v83, -v87, s53, v83
	v_fma_f32 v84, -v88, s53, v84
	v_fma_f32 v85, -v89, s53, v85
	s_mov_b32 s84, 0x3f000000
	v_lshlrev_b32_e32 v86, 16, v30
	v_and_b32_e32 v87, 0xffff0000, v30
	v_lshlrev_b32_e32 v88, 16, v31
	v_and_b32_e32 v89, 0xffff0000, v31
	v_mul_f32_e32 v86, s55, v86
	v_mul_f32_e32 v87, s55, v87
	v_mul_f32_e32 v88, s55, v88
	v_mul_f32_e32 v89, s55, v89
	v_fma_f32 v90, v82, s84, -v86
	v_fma_f32 v91, v83, s84, -v87
	v_fma_f32 v92, v84, s84, -v88
	v_fma_f32 v93, v85, s84, -v89
	v_cvt_pk_bf16_f32 v94, v90, v91
	v_cvt_pk_bf16_f32 v95, v92, v93
	global_store_dwordx2 v62, v[94:95], s[2:3]
	s_add_u32 s2, s2, 0x800
	s_addc_u32 s3, s3, 0
	s_waitcnt vmcnt(15)
	v_lshlrev_b32_e32 v86, 16, v32
	v_and_b32_e32 v87, 0xffff0000, v32
	v_lshlrev_b32_e32 v88, 16, v33
	v_and_b32_e32 v89, 0xffff0000, v33
	v_fmac_f32_e32 v82, s56, v86
	v_fmac_f32_e32 v83, s56, v87
	v_fmac_f32_e32 v84, s56, v88
	v_fmac_f32_e32 v85, s56, v89
	v_lshlrev_b32_e32 v86, 16, v28
	v_and_b32_e32 v87, 0xffff0000, v28
	v_lshlrev_b32_e32 v88, 16, v29
	v_and_b32_e32 v89, 0xffff0000, v29
	v_fma_f32 v82, -v86, s54, v82
	v_fma_f32 v83, -v87, s54, v83
	v_fma_f32 v84, -v88, s54, v84
	v_fma_f32 v85, -v89, s54, v85
	s_mov_b32 s84, 0x3f000000
	v_lshlrev_b32_e32 v86, 16, v32
	v_and_b32_e32 v87, 0xffff0000, v32
	v_lshlrev_b32_e32 v88, 16, v33
	v_and_b32_e32 v89, 0xffff0000, v33
	v_mul_f32_e32 v86, s56, v86
	v_mul_f32_e32 v87, s56, v87
	v_mul_f32_e32 v88, s56, v88
	v_mul_f32_e32 v89, s56, v89
	v_fma_f32 v90, v82, s84, -v86
	v_fma_f32 v91, v83, s84, -v87
	v_fma_f32 v92, v84, s84, -v88
	v_fma_f32 v93, v85, s84, -v89
	v_cvt_pk_bf16_f32 v94, v90, v91
	v_cvt_pk_bf16_f32 v95, v92, v93
	global_store_dwordx2 v62, v[94:95], s[2:3]
	s_branch .Lpool_next
.Lpool_g1:
	s_sub_i32 s84, s83, 2
	v_add_u32_e32 v64, s84, v205
	s_cmp_lg_u32 s86, 0
	s_cselect_b32 s85, 2, 0
	s_cmp_lg_u32 s87, 0
	s_cselect_b32 s101, 18, 19
	v_cmp_le_u32_e64 s[4:5], s85, v205
	v_cmp_gt_u32_e32 vcc, s101, v205
	s_and_b64 vcc, vcc, s[4:5]
	v_mov_b32_e32 v65, s83
	v_cndmask_b32_e32 v64, v65, v64, vcc
	v_lshlrev_b32_e32 v64, 6, v64
	s_add_u32 s2, s80, 0x13648000
	s_addc_u32 s3, s81, 0
	global_load_dwordx4 v[66:69], v64, s[2:3]
	global_load_dwordx4 v[70:73], v64, s[2:3] offset:16
	global_load_dwordx4 v[74:77], v64, s[2:3] offset:32
	global_load_dwordx4 v[78:81], v64, s[2:3] offset:48
	s_add_u32 s2, s80, 0x87c8200
	s_addc_u32 s3, s81, 0
	s_lshl_b32 s85, s83, 11
	s_add_u32 s4, s2, s85
	s_addc_u32 s5, s3, 0
	s_sub_u32 s2, s4, 0x1000
	s_subb_u32 s3, s5, 0
	s_cmp_lg_u32 s86, 0
	s_cselect_b64 s[84:85], s[4:5], s[2:3]
	global_load_dwordx2 v[0:1], v62, s[84:85]
	s_add_u32 s2, s2, 0x800
	s_addc_u32 s3, s3, 0
	s_cmp_lg_u32 s86, 0
	s_cselect_b64 s[84:85], s[4:5], s[2:3]
	global_load_dwordx2 v[2:3], v62, s[84:85]
	s_add_u32 s2, s2, 0x800
	s_addc_u32 s3, s3, 0
	global_load_dwordx2 v[4:5], v62, s[2:3]
	s_add_u32 s2, s2, 0x800
	s_addc_u32 s3, s3, 0
	global_load_dwordx2 v[6:7], v62, s[2:3]
	s_add_u32 s2, s2, 0x800
	s_addc_u32 s3, s3, 0
	global_load_dwordx2 v[8:9], v62, s[2:3]
	s_add_u32 s2, s2, 0x800
	s_addc_u32 s3, s3, 0
	global_load_dwordx2 v[10:11], v62, s[2:3]
	s_add_u32 s2, s2, 0x800
	s_addc_u32 s3, s3, 0
	global_load_dwordx2 v[12:13], v62, s[2:3]
	s_add_u32 s2, s2, 0x800
	s_addc_u32 s3, s3, 0
	global_load_dwordx2 v[14:15], v62, s[2:3]
	s_add_u32 s2, s2, 0x800
	s_addc_u32 s3, s3, 0
	global_load_dwordx2 v[16:17], v62, s[2:3]
	s_add_u32 s2, s2, 0x800
	s_addc_u32 s3, s3, 0
	global_load_dwordx2 v[18:19], v62, s[2:3]
	s_add_u32 s2, s2, 0x800
	s_addc_u32 s3, s3, 0
	global_load_dwordx2 v[20:21], v62, s[2:3]
	s_add_u32 s2, s2, 0x800
	s_addc_u32 s3, s3, 0
	global_load_dwordx2 v[22:23], v62, s[2:3]
	s_add_u32 s2, s2, 0x800
	s_addc_u32 s3, s3, 0
	global_load_dwordx2 v[24:25], v62, s[2:3]
	s_add_u32 s2, s2, 0x800
	s_addc_u32 s3, s3, 0
	global_load_dwordx2 v[26:27], v62, s[2:3]
	s_add_u32 s2, s2, 0x800
	s_addc_u32 s3, s3, 0
	global_load_dwordx2 v[28:29], v62, s[2:3]
	s_add_u32 s2, s2, 0x800
	s_addc_u32 s3, s3, 0
	global_load_dwordx2 v[30:31], v62, s[2:3]
	s_add_u32 s2, s2, 0x800
	s_addc_u32 s3, s3, 0
	global_load_dwordx2 v[32:33], v62, s[2:3]
	s_add_u32 s2, s2, 0x800
	s_addc_u32 s3, s3, 0
	global_load_dwordx2 v[34:35], v62, s[2:3]
	s_add_u32 s2, s2, 0x800
	s_addc_u32 s3, s3, 0
	s_cmp_lg_u32 s87, 0
	s_cselect_b64 s[84:85], s[4:5], s[2:3]
	global_load_dwordx2 v[36:37], v62, s[84:85]
	s_waitcnt vmcnt(19)
	v_add_f32_e32 v66, v66, v67
	v_add_f32_e32 v68, v68, v69
	v_add_f32_e32 v70, v70, v71
	v_add_f32_e32 v72, v72, v73
	v_add_f32_e32 v74, v74, v75
	v_add_f32_e32 v76, v76, v77
	v_add_f32_e32 v78, v78, v79
	v_add_f32_e32 v80, v80, v81
	v_add_f32_e32 v66, v66, v68
	v_add_f32_e32 v70, v70, v72
	v_add_f32_e32 v74, v74, v76
	v_add_f32_e32 v78, v78, v80
	v_add_f32_e32 v66, v66, v70
	v_add_f32_e32 v74, v74, v78
	v_add_f32_e32 v66, v66, v74
	v_fmamk_f32 v66, v66, 0x3a800000, v207
	v_rsq_f32_e32 v66, v66
	s_nop 0
	v_cndmask_b32_e32 v63, 0, v66, vcc
	s_nop 1
	v_readlane_b32 s40, v63, 0
	v_readlane_b32 s41, v63, 1
	v_readlane_b32 s42, v63, 2
	v_readlane_b32 s43, v63, 3
	v_readlane_b32 s44, v63, 4
	v_readlane_b32 s45, v63, 5
	v_readlane_b32 s46, v63, 6
	v_readlane_b32 s47, v63, 7
	v_readlane_b32 s48, v63, 8
	v_readlane_b32 s49, v63, 9
	v_readlane_b32 s50, v63, 10
	v_readlane_b32 s51, v63, 11
	v_readlane_b32 s52, v63, 12
	v_readlane_b32 s53, v63, 13
	v_readlane_b32 s54, v63, 14
	v_readlane_b32 s55, v63, 15
	v_readlane_b32 s56, v63, 16
	v_readlane_b32 s57, v63, 17
	v_readlane_b32 s58, v63, 18
	s_add_u32 s2, s80, 0x9fc8200
	s_addc_u32 s3, s81, 0
	s_lshl_b32 s85, s83, 11
	s_add_u32 s2, s2, s85
	s_addc_u32 s3, s3, 0
	s_waitcnt vmcnt(15)
	v_lshlrev_b32_e32 v86, 16, v0
	v_and_b32_e32 v87, 0xffff0000, v0
	v_lshlrev_b32_e32 v88, 16, v1
	v_and_b32_e32 v89, 0xffff0000, v1
	v_mul_f32_e32 v82, s40, v86
	v_mul_f32_e32 v83, s40, v87
	v_mul_f32_e32 v84, s40, v88
	v_mul_f32_e32 v85, s40, v89
	v_lshlrev_b32_e32 v86, 16, v2
	v_and_b32_e32 v87, 0xffff0000, v2
	v_lshlrev_b32_e32 v88, 16, v3
	v_and_b32_e32 v89, 0xffff0000, v3
	v_fmac_f32_e32 v82, s41, v86
	v_fmac_f32_e32 v83, s41, v87
	v_fmac_f32_e32 v84, s41, v88
	v_fmac_f32_e32 v85, s41, v89
	v_lshlrev_b32_e32 v86, 16, v4
	v_and_b32_e32 v87, 0xffff0000, v4
	v_lshlrev_b32_e32 v88, 16, v5
	v_and_b32_e32 v89, 0xffff0000, v5
	v_fmac_f32_e32 v82, s42, v86
	v_fmac_f32_e32 v83, s42, v87
	v_fmac_f32_e32 v84, s42, v88
	v_fmac_f32_e32 v85, s42, v89
	v_lshlrev_b32_e32 v86, 16, v6
	v_and_b32_e32 v87, 0xffff0000, v6
	v_lshlrev_b32_e32 v88, 16, v7
	v_and_b32_e32 v89, 0xffff0000, v7
	v_fmac_f32_e32 v82, s43, v86
	v_fmac_f32_e32 v83, s43, v87
	v_fmac_f32_e32 v84, s43, v88
	v_fmac_f32_e32 v85, s43, v89
	s_cmp_lg_u32 s86, 0
	s_mov_b32 s84, 0x3e800000
	s_cselect_b32 s84, 0x3f000000, s84
	v_lshlrev_b32_e32 v86, 16, v4
	v_and_b32_e32 v87, 0xffff0000, v4
	v_lshlrev_b32_e32 v88, 16, v5
	v_and_b32_e32 v89, 0xffff0000, v5
	v_mul_f32_e32 v86, s42, v86
	v_mul_f32_e32 v87, s42, v87
	v_mul_f32_e32 v88, s42, v88
	v_mul_f32_e32 v89, s42, v89
	v_fma_f32 v90, v82, s84, -v86
	v_fma_f32 v91, v83, s84, -v87
	v_fma_f32 v92, v84, s84, -v88
	v_fma_f32 v93, v85, s84, -v89
	v_cvt_pk_bf16_f32 v94, v90, v91
	v_cvt_pk_bf16_f32 v95, v92, v93
	global_store_dwordx2 v62, v[94:95], s[2:3]
	s_add_u32 s2, s2, 0x800
	s_addc_u32 s3, s3, 0
	s_waitcnt vmcnt(15)
	v_lshlrev_b32_e32 v86, 16, v8
	v_and_b32_e32 v87, 0xffff0000, v8
	v_lshlrev_b32_e32 v88, 16, v9
	v_and_b32_e32 v89, 0xffff0000, v9
	v_fmac_f32_e32 v82, s44, v86
	v_fmac_f32_e32 v83, s44, v87
	v_fmac_f32_e32 v84, s44, v88
	v_fmac_f32_e32 v85, s44, v89
	v_lshlrev_b32_e32 v86, 16, v0
	v_and_b32_e32 v87, 0xffff0000, v0
	v_lshlrev_b32_e32 v88, 16, v1
	v_and_b32_e32 v89, 0xffff0000, v1
	v_fma_f32 v82, -v86, s40, v82
	v_fma_f32 v83, -v87, s40, v83
	v_fma_f32 v84, -v88, s40, v84
	v_fma_f32 v85, -v89, s40, v85
	s_cmp_lg_u32 s86, 0
	s_mov_b32 s84, 0x3e800000
	s_cselect_b32 s84, 0x3eaaaaab, s84
	v_lshlrev_b32_e32 v86, 16, v6
	v_and_b32_e32 v87, 0xffff0000, v6
	v_lshlrev_b32_e32 v88, 16, v7
	v_and_b32_e32 v89, 0xffff0000, v7
	v_mul_f32_e32 v86, s43, v86
	v_mul_f32_e32 v87, s43, v87
	v_mul_f32_e32 v88, s43, v88
	v_mul_f32_e32 v89, s43, v89
	v_fma_f32 v90, v82, s84, -v86
	v_fma_f32 v91, v83, s84, -v87
	v_fma_f32 v92, v84, s84, -v88
	v_fma_f32 v93, v85, s84, -v89
	v_cvt_pk_bf16_f32 v94, v90, v91
	v_cvt_pk_bf16_f32 v95, v92, v93
	global_store_dwordx2 v62, v[94:95], s[2:3]
	s_add_u32 s2, s2, 0x800
	s_addc_u32 s3, s3, 0
	s_waitcnt vmcnt(15)
	v_lshlrev_b32_e32 v86, 16, v10
	v_and_b32_e32 v87, 0xffff0000, v10
	v_lshlrev_b32_e32 v88, 16, v11
	v_and_b32_e32 v89, 0xffff0000, v11
	v_fmac_f32_e32 v82, s45, v86
	v_fmac_f32_e32 v83, s45, v87
	v_fmac_f32_e32 v84, s45, v88
	v_fmac_f32_e32 v85, s45, v89
	v_lshlrev_b32_e32 v86, 16, v2
	v_and_b32_e32 v87, 0xffff0000, v2
	v_lshlrev_b32_e32 v88, 16, v3
	v_and_b32_e32 v89, 0xffff0000, v3
	v_fma_f32 v82, -v86, s41, v82
	v_fma_f32 v83, -v87, s41, v83
	v_fma_f32 v84, -v88, s41, v84
	v_fma_f32 v85, -v89, s41, v85
	s_mov_b32 s84, 0x3e800000
	v_lshlrev_b32_e32 v86, 16, v8
	v_and_b32_e32 v87, 0xffff0000, v8
	v_lshlrev_b32_e32 v88, 16, v9
	v_and_b32_e32 v89, 0xffff0000, v9
	v_mul_f32_e32 v86, s44, v86
	v_mul_f32_e32 v87, s44, v87
	v_mul_f32_e32 v88, s44, v88
	v_mul_f32_e32 v89, s44, v89
	v_fma_f32 v90, v82, s84, -v86
	v_fma_f32 v91, v83, s84, -v87
	v_fma_f32 v92, v84, s84, -v88
	v_fma_f32 v93, v85, s84, -v89
	v_cvt_pk_bf16_f32 v94, v90, v91
	v_cvt_pk_bf16_f32 v95, v92, v93
	global_store_dwordx2 v62, v[94:95], s[2:3]
	s_add_u32 s2, s2, 0x800
	s_addc_u32 s3, s3, 0
	s_waitcnt vmcnt(15)
	v_lshlrev_b32_e32 v86, 16, v12
	v_and_b32_e32 v87, 0xffff0000, v12
	v_lshlrev_b32_e32 v88, 16, v13
	v_and_b32_e32 v89, 0xffff0000, v13
	v_fmac_f32_e32 v82, s46, v86
	v_fmac_f32_e32 v83, s46, v87
	v_fmac_f32_e32 v84, s46, v88
	v_fmac_f32_e32 v85, s46, v89
	v_lshlrev_b32_e32 v86, 16, v4
	v_and_b32_e32 v87, 0xffff0000, v4
	v_lshlrev_b32_e32 v88, 16, v5
	v_and_b32_e32 v89, 0xffff0000, v5
	v_fma_f32 v82, -v86, s42, v82
	v_fma_f32 v83, -v87, s42, v83
	v_fma_f32 v84, -v88, s42, v84
	v_fma_f32 v85, -v89, s42, v85
	s_mov_b32 s84, 0x3e800000
	v_lshlrev_b32_e32 v86, 16, v10
	v_and_b32_e32 v87, 0xffff0000, v10
	v_lshlrev_b32_e32 v88, 16, v11
	v_and_b32_e32 v89, 0xffff0000, v11
	v_mul_f32_e32 v86, s45, v86
	v_mul_f32_e32 v87, s45, v87
	v_mul_f32_e32 v88, s45, v88
	v_mul_f32_e32 v89, s45, v89
	v_fma_f32 v90, v82, s84, -v86
	v_fma_f32 v91, v83, s84, -v87
	v_fma_f32 v92, v84, s84, -v88
	v_fma_f32 v93, v85, s84, -v89
	v_cvt_pk_bf16_f32 v94, v90, v91
	v_cvt_pk_bf16_f32 v95, v92, v93
	global_store_dwordx2 v62, v[94:95], s[2:3]
	s_add_u32 s2, s2, 0x800
	s_addc_u32 s3, s3, 0
	s_waitcnt vmcnt(15)
	v_lshlrev_b32_e32 v86, 16, v14
	v_and_b32_e32 v87, 0xffff0000, v14
	v_lshlrev_b32_e32 v88, 16, v15
	v_and_b32_e32 v89, 0xffff0000, v15
	v_fmac_f32_e32 v82, s47, v86
	v_fmac_f32_e32 v83, s47, v87
	v_fmac_f32_e32 v84, s47, v88
	v_fmac_f32_e32 v85, s47, v89
	v_lshlrev_b32_e32 v86, 16, v6
	v_and_b32_e32 v87, 0xffff0000, v6
	v_lshlrev_b32_e32 v88, 16, v7
	v_and_b32_e32 v89, 0xffff0000, v7
	v_fma_f32 v82, -v86, s43, v82
	v_fma_f32 v83, -v87, s43, v83
	v_fma_f32 v84, -v88, s43, v84
	v_fma_f32 v85, -v89, s43, v85
	s_mov_b32 s84, 0x3e800000
	v_lshlrev_b32_e32 v86, 16, v12
	v_and_b32_e32 v87, 0xffff0000, v12
	v_lshlrev_b32_e32 v88, 16, v13
	v_and_b32_e32 v89, 0xffff0000, v13
	v_mul_f32_e32 v86, s46, v86
	v_mul_f32_e32 v87, s46, v87
	v_mul_f32_e32 v88, s46, v88
	v_mul_f32_e32 v89, s46, v89
	v_fma_f32 v90, v82, s84, -v86
	v_fma_f32 v91, v83, s84, -v87
	v_fma_f32 v92, v84, s84, -v88
	v_fma_f32 v93, v85, s84, -v89
	v_cvt_pk_bf16_f32 v94, v90, v91
	v_cvt_pk_bf16_f32 v95, v92, v93
	global_store_dwordx2 v62, v[94:95], s[2:3]
	s_add_u32 s2, s2, 0x800
	s_addc_u32 s3, s3, 0
	s_waitcnt vmcnt(15)
	v_lshlrev_b32_e32 v86, 16, v16
	v_and_b32_e32 v87, 0xffff0000, v16
	v_lshlrev_b32_e32 v88, 16, v17
	v_and_b32_e32 v89, 0xffff0000, v17
	v_fmac_f32_e32 v82, s48, v86
	v_fmac_f32_e32 v83, s48, v87
	v_fmac_f32_e32 v84, s48, v88
	v_fmac_f32_e32 v85, s48, v89
	v_lshlrev_b32_e32 v86, 16, v8
	v_and_b32_e32 v87, 0xffff0000, v8
	v_lshlrev_b32_e32 v88, 16, v9
	v_and_b32_e32 v89, 0xffff0000, v9
	v_fma_f32 v82, -v86, s44, v82
	v_fma_f32 v83, -v87, s44, v83
	v_fma_f32 v84, -v88, s44, v84
	v_fma_f32 v85, -v89, s44, v85
	s_mov_b32 s84, 0x3e800000
	v_lshlrev_b32_e32 v86, 16, v14
	v_and_b32_e32 v87, 0xffff0000, v14
	v_lshlrev_b32_e32 v88, 16, v15
	v_and_b32_e32 v89, 0xffff0000, v15
	v_mul_f32_e32 v86, s47, v86
	v_mul_f32_e32 v87, s47, v87
	v_mul_f32_e32 v88, s47, v88
	v_mul_f32_e32 v89, s47, v89
	v_fma_f32 v90, v82, s84, -v86
	v_fma_f32 v91, v83, s84, -v87
	v_fma_f32 v92, v84, s84, -v88
	v_fma_f32 v93, v85, s84, -v89
	v_cvt_pk_bf16_f32 v94, v90, v91
	v_cvt_pk_bf16_f32 v95, v92, v93
	global_store_dwordx2 v62, v[94:95], s[2:3]
	s_add_u32 s2, s2, 0x800
	s_addc_u32 s3, s3, 0
	s_waitcnt vmcnt(15)
	v_lshlrev_b32_e32 v86, 16, v18
	v_and_b32_e32 v87, 0xffff0000, v18
	v_lshlrev_b32_e32 v88, 16, v19
	v_and_b32_e32 v89, 0xffff0000, v19
	v_fmac_f32_e32 v82, s49, v86
	v_fmac_f32_e32 v83, s49, v87
	v_fmac_f32_e32 v84, s49, v88
	v_fmac_f32_e32 v85, s49, v89
	v_lshlrev_b32_e32 v86, 16, v10
	v_and_b32_e32 v87, 0xffff0000, v10
	v_lshlrev_b32_e32 v88, 16, v11
	v_and_b32_e32 v89, 0xffff0000, v11
	v_fma_f32 v82, -v86, s45, v82
	v_fma_f32 v83, -v87, s45, v83
	v_fma_f32 v84, -v88, s45, v84
	v_fma_f32 v85, -v89, s45, v85
	s_mov_b32 s84, 0x3e800000
	v_lshlrev_b32_e32 v86, 16, v16
	v_and_b32_e32 v87, 0xffff0000, v16
	v_lshlrev_b32_e32 v88, 16, v17
	v_and_b32_e32 v89, 0xffff0000, v17
	v_mul_f32_e32 v86, s48, v86
	v_mul_f32_e32 v87, s48, v87
	v_mul_f32_e32 v88, s48, v88
	v_mul_f32_e32 v89, s48, v89
	v_fma_f32 v90, v82, s84, -v86
	v_fma_f32 v91, v83, s84, -v87
	v_fma_f32 v92, v84, s84, -v88
	v_fma_f32 v93, v85, s84, -v89
	v_cvt_pk_bf16_f32 v94, v90, v91
	v_cvt_pk_bf16_f32 v95, v92, v93
	global_store_dwordx2 v62, v[94:95], s[2:3]
	s_add_u32 s2, s2, 0x800
	s_addc_u32 s3, s3, 0
	s_waitcnt vmcnt(15)
	v_lshlrev_b32_e32 v86, 16, v20
	v_and_b32_e32 v87, 0xffff0000, v20
	v_lshlrev_b32_e32 v88, 16, v21
	v_and_b32_e32 v89, 0xffff0000, v21
	v_fmac_f32_e32 v82, s50, v86
	v_fmac_f32_e32 v83, s50, v87
	v_fmac_f32_e32 v84, s50, v88
	v_fmac_f32_e32 v85, s50, v89
	v_lshlrev_b32_e32 v86, 16, v12
	v_and_b32_e32 v87, 0xffff0000, v12
	v_lshlrev_b32_e32 v88, 16, v13
	v_and_b32_e32 v89, 0xffff0000, v13
	v_fma_f32 v82, -v86, s46, v82
	v_fma_f32 v83, -v87, s46, v83
	v_fma_f32 v84, -v88, s46, v84
	v_fma_f32 v85, -v89, s46, v85
	s_mov_b32 s84, 0x3e800000
	v_lshlrev_b32_e32 v86, 16, v18
	v_and_b32_e32 v87, 0xffff0000, v18
	v_lshlrev_b32_e32 v88, 16, v19
	v_and_b32_e32 v89, 0xffff0000, v19
	v_mul_f32_e32 v86, s49, v86
	v_mul_f32_e32 v87, s49, v87
	v_mul_f32_e32 v88, s49, v88
	v_mul_f32_e32 v89, s49, v89
	v_fma_f32 v90, v82, s84, -v86
	v_fma_f32 v91, v83, s84, -v87
	v_fma_f32 v92, v84, s84, -v88
	v_fma_f32 v93, v85, s84, -v89
	v_cvt_pk_bf16_f32 v94, v90, v91
	v_cvt_pk_bf16_f32 v95, v92, v93
	global_store_dwordx2 v62, v[94:95], s[2:3]
	s_add_u32 s2, s2, 0x800
	s_addc_u32 s3, s3, 0
	s_waitcnt vmcnt(15)
	v_lshlrev_b32_e32 v86, 16, v22
	v_and_b32_e32 v87, 0xffff0000, v22
	v_lshlrev_b32_e32 v88, 16, v23
	v_and_b32_e32 v89, 0xffff0000, v23
	v_fmac_f32_e32 v82, s51, v86
	v_fmac_f32_e32 v83, s51, v87
	v_fmac_f32_e32 v84, s51, v88
	v_fmac_f32_e32 v85, s51, v89
	v_lshlrev_b32_e32 v86, 16, v14
	v_and_b32_e32 v87, 0xffff0000, v14
	v_lshlrev_b32_e32 v88, 16, v15
	v_and_b32_e32 v89, 0xffff0000, v15
	v_fma_f32 v82, -v86, s47, v82
	v_fma_f32 v83, -v87, s47, v83
	v_fma_f32 v84, -v88, s47, v84
	v_fma_f32 v85, -v89, s47, v85
	s_mov_b32 s84, 0x3e800000
	v_lshlrev_b32_e32 v86, 16, v20
	v_and_b32_e32 v87, 0xffff0000, v20
	v_lshlrev_b32_e32 v88, 16, v21
	v_and_b32_e32 v89, 0xffff0000, v21
	v_mul_f32_e32 v86, s50, v86
	v_mul_f32_e32 v87, s50, v87
	v_mul_f32_e32 v88, s50, v88
	v_mul_f32_e32 v89, s50, v89
	v_fma_f32 v90, v82, s84, -v86
	v_fma_f32 v91, v83, s84, -v87
	v_fma_f32 v92, v84, s84, -v88
	v_fma_f32 v93, v85, s84, -v89
	v_cvt_pk_bf16_f32 v94, v90, v91
	v_cvt_pk_bf16_f32 v95, v92, v93
	global_store_dwordx2 v62, v[94:95], s[2:3]
	s_add_u32 s2, s2, 0x800
	s_addc_u32 s3, s3, 0
	s_waitcnt vmcnt(15)
	v_lshlrev_b32_e32 v86, 16, v24
	v_and_b32_e32 v87, 0xffff0000, v24
	v_lshlrev_b32_e32 v88, 16, v25
	v_and_b32_e32 v89, 0xffff0000, v25
	v_fmac_f32_e32 v82, s52, v86
	v_fmac_f32_e32 v83, s52, v87
	v_fmac_f32_e32 v84, s52, v88
	v_fmac_f32_e32 v85, s52, v89
	v_lshlrev_b32_e32 v86, 16, v16
	v_and_b32_e32 v87, 0xffff0000, v16
	v_lshlrev_b32_e32 v88, 16, v17
	v_and_b32_e32 v89, 0xffff0000, v17
	v_fma_f32 v82, -v86, s48, v82
	v_fma_f32 v83, -v87, s48, v83
	v_fma_f32 v84, -v88, s48, v84
	v_fma_f32 v85, -v89, s48, v85
	s_mov_b32 s84, 0x3e800000
	v_lshlrev_b32_e32 v86, 16, v22
	v_and_b32_e32 v87, 0xffff0000, v22
	v_lshlrev_b32_e32 v88, 16, v23
	v_and_b32_e32 v89, 0xffff0000, v23
	v_mul_f32_e32 v86, s51, v86
	v_mul_f32_e32 v87, s51, v87
	v_mul_f32_e32 v88, s51, v88
	v_mul_f32_e32 v89, s51, v89
	v_fma_f32 v90, v82, s84, -v86
	v_fma_f32 v91, v83, s84, -v87
	v_fma_f32 v92, v84, s84, -v88
	v_fma_f32 v93, v85, s84, -v89
	v_cvt_pk_bf16_f32 v94, v90, v91
	v_cvt_pk_bf16_f32 v95, v92, v93
	global_store_dwordx2 v62, v[94:95], s[2:3]
	s_add_u32 s2, s2, 0x800
	s_addc_u32 s3, s3, 0
	s_waitcnt vmcnt(15)
	v_lshlrev_b32_e32 v86, 16, v26
	v_and_b32_e32 v87, 0xffff0000, v26
	v_lshlrev_b32_e32 v88, 16, v27
	v_and_b32_e32 v89, 0xffff0000, v27
	v_fmac_f32_e32 v82, s53, v86
	v_fmac_f32_e32 v83, s53, v87
	v_fmac_f32_e32 v84, s53, v88
	v_fmac_f32_e32 v85, s53, v89
	v_lshlrev_b32_e32 v86, 16, v18
	v_and_b32_e32 v87, 0xffff0000, v18
	v_lshlrev_b32_e32 v88, 16, v19
	v_and_b32_e32 v89, 0xffff0000, v19
	v_fma_f32 v82, -v86, s49, v82
	v_fma_f32 v83, -v87, s49, v83
	v_fma_f32 v84, -v88, s49, v84
	v_fma_f32 v85, -v89, s49, v85
	s_mov_b32 s84, 0x3e800000
	v_lshlrev_b32_e32 v86, 16, v24
	v_and_b32_e32 v87, 0xffff0000, v24
	v_lshlrev_b32_e32 v88, 16, v25
	v_and_b32_e32 v89, 0xffff0000, v25
	v_mul_f32_e32 v86, s52, v86
	v_mul_f32_e32 v87, s52, v87
	v_mul_f32_e32 v88, s52, v88
	v_mul_f32_e32 v89, s52, v89
	v_fma_f32 v90, v82, s84, -v86
	v_fma_f32 v91, v83, s84, -v87
	v_fma_f32 v92, v84, s84, -v88
	v_fma_f32 v93, v85, s84, -v89
	v_cvt_pk_bf16_f32 v94, v90, v91
	v_cvt_pk_bf16_f32 v95, v92, v93
	global_store_dwordx2 v62, v[94:95], s[2:3]
	s_add_u32 s2, s2, 0x800
	s_addc_u32 s3, s3, 0
	s_waitcnt vmcnt(15)
	v_lshlrev_b32_e32 v86, 16, v28
	v_and_b32_e32 v87, 0xffff0000, v28
	v_lshlrev_b32_e32 v88, 16, v29
	v_and_b32_e32 v89, 0xffff0000, v29
	v_fmac_f32_e32 v82, s54, v86
	v_fmac_f32_e32 v83, s54, v87
	v_fmac_f32_e32 v84, s54, v88
	v_fmac_f32_e32 v85, s54, v89
	v_lshlrev_b32_e32 v86, 16, v20
	v_and_b32_e32 v87, 0xffff0000, v20
	v_lshlrev_b32_e32 v88, 16, v21
	v_and_b32_e32 v89, 0xffff0000, v21
	v_fma_f32 v82, -v86, s50, v82
	v_fma_f32 v83, -v87, s50, v83
	v_fma_f32 v84, -v88, s50, v84
	v_fma_f32 v85, -v89, s50, v85
	s_mov_b32 s84, 0x3e800000
	v_lshlrev_b32_e32 v86, 16, v26
	v_and_b32_e32 v87, 0xffff0000, v26
	v_lshlrev_b32_e32 v88, 16, v27
	v_and_b32_e32 v89, 0xffff0000, v27
	v_mul_f32_e32 v86, s53, v86
	v_mul_f32_e32 v87, s53, v87
	v_mul_f32_e32 v88, s53, v88
	v_mul_f32_e32 v89, s53, v89
	v_fma_f32 v90, v82, s84, -v86
	v_fma_f32 v91, v83, s84, -v87
	v_fma_f32 v92, v84, s84, -v88
	v_fma_f32 v93, v85, s84, -v89
	v_cvt_pk_bf16_f32 v94, v90, v91
	v_cvt_pk_bf16_f32 v95, v92, v93
	global_store_dwordx2 v62, v[94:95], s[2:3]
	s_add_u32 s2, s2, 0x800
	s_addc_u32 s3, s3, 0
	s_waitcnt vmcnt(15)
	v_lshlrev_b32_e32 v86, 16, v30
	v_and_b32_e32 v87, 0xffff0000, v30
	v_lshlrev_b32_e32 v88, 16, v31
	v_and_b32_e32 v89, 0xffff0000, v31
	v_fmac_f32_e32 v82, s55, v86
	v_fmac_f32_e32 v83, s55, v87
	v_fmac_f32_e32 v84, s55, v88
	v_fmac_f32_e32 v85, s55, v89
	v_lshlrev_b32_e32 v86, 16, v22
	v_and_b32_e32 v87, 0xffff0000, v22
	v_lshlrev_b32_e32 v88, 16, v23
	v_and_b32_e32 v89, 0xffff0000, v23
	v_fma_f32 v82, -v86, s51, v82
	v_fma_f32 v83, -v87, s51, v83
	v_fma_f32 v84, -v88, s51, v84
	v_fma_f32 v85, -v89, s51, v85
	s_mov_b32 s84, 0x3e800000
	v_lshlrev_b32_e32 v86, 16, v28
	v_and_b32_e32 v87, 0xffff0000, v28
	v_lshlrev_b32_e32 v88, 16, v29
	v_and_b32_e32 v89, 0xffff0000, v29
	v_mul_f32_e32 v86, s54, v86
	v_mul_f32_e32 v87, s54, v87
	v_mul_f32_e32 v88, s54, v88
	v_mul_f32_e32 v89, s54, v89
	v_fma_f32 v90, v82, s84, -v86
	v_fma_f32 v91, v83, s84, -v87
	v_fma_f32 v92, v84, s84, -v88
	v_fma_f32 v93, v85, s84, -v89
	v_cvt_pk_bf16_f32 v94, v90, v91
	v_cvt_pk_bf16_f32 v95, v92, v93
	global_store_dwordx2 v62, v[94:95], s[2:3]
	s_add_u32 s2, s2, 0x800
	s_addc_u32 s3, s3, 0
	s_waitcnt vmcnt(15)
	v_lshlrev_b32_e32 v86, 16, v32
	v_and_b32_e32 v87, 0xffff0000, v32
	v_lshlrev_b32_e32 v88, 16, v33
	v_and_b32_e32 v89, 0xffff0000, v33
	v_fmac_f32_e32 v82, s56, v86
	v_fmac_f32_e32 v83, s56, v87
	v_fmac_f32_e32 v84, s56, v88
	v_fmac_f32_e32 v85, s56, v89
	v_lshlrev_b32_e32 v86, 16, v24
	v_and_b32_e32 v87, 0xffff0000, v24
	v_lshlrev_b32_e32 v88, 16, v25
	v_and_b32_e32 v89, 0xffff0000, v25
	v_fma_f32 v82, -v86, s52, v82
	v_fma_f32 v83, -v87, s52, v83
	v_fma_f32 v84, -v88, s52, v84
	v_fma_f32 v85, -v89, s52, v85
	s_mov_b32 s84, 0x3e800000
	v_lshlrev_b32_e32 v86, 16, v30
	v_and_b32_e32 v87, 0xffff0000, v30
	v_lshlrev_b32_e32 v88, 16, v31
	v_and_b32_e32 v89, 0xffff0000, v31
	v_mul_f32_e32 v86, s55, v86
	v_mul_f32_e32 v87, s55, v87
	v_mul_f32_e32 v88, s55, v88
	v_mul_f32_e32 v89, s55, v89
	v_fma_f32 v90, v82, s84, -v86
	v_fma_f32 v91, v83, s84, -v87
	v_fma_f32 v92, v84, s84, -v88
	v_fma_f32 v93, v85, s84, -v89
	v_cvt_pk_bf16_f32 v94, v90, v91
	v_cvt_pk_bf16_f32 v95, v92, v93
	global_store_dwordx2 v62, v[94:95], s[2:3]
	s_add_u32 s2, s2, 0x800
	s_addc_u32 s3, s3, 0
	s_waitcnt vmcnt(15)
	v_lshlrev_b32_e32 v86, 16, v34
	v_and_b32_e32 v87, 0xffff0000, v34
	v_lshlrev_b32_e32 v88, 16, v35
	v_and_b32_e32 v89, 0xffff0000, v35
	v_fmac_f32_e32 v82, s57, v86
	v_fmac_f32_e32 v83, s57, v87
	v_fmac_f32_e32 v84, s57, v88
	v_fmac_f32_e32 v85, s57, v89
	v_lshlrev_b32_e32 v86, 16, v26
	v_and_b32_e32 v87, 0xffff0000, v26
	v_lshlrev_b32_e32 v88, 16, v27
	v_and_b32_e32 v89, 0xffff0000, v27
	v_fma_f32 v82, -v86, s53, v82
	v_fma_f32 v83, -v87, s53, v83
	v_fma_f32 v84, -v88, s53, v84
	v_fma_f32 v85, -v89, s53, v85
	s_mov_b32 s84, 0x3e800000
	v_lshlrev_b32_e32 v86, 16, v32
	v_and_b32_e32 v87, 0xffff0000, v32
	v_lshlrev_b32_e32 v88, 16, v33
	v_and_b32_e32 v89, 0xffff0000, v33
	v_mul_f32_e32 v86, s56, v86
	v_mul_f32_e32 v87, s56, v87
	v_mul_f32_e32 v88, s56, v88
	v_mul_f32_e32 v89, s56, v89
	v_fma_f32 v90, v82, s84, -v86
	v_fma_f32 v91, v83, s84, -v87
	v_fma_f32 v92, v84, s84, -v88
	v_fma_f32 v93, v85, s84, -v89
	v_cvt_pk_bf16_f32 v94, v90, v91
	v_cvt_pk_bf16_f32 v95, v92, v93
	global_store_dwordx2 v62, v[94:95], s[2:3]
	s_add_u32 s2, s2, 0x800
	s_addc_u32 s3, s3, 0
	s_waitcnt vmcnt(15)
	v_lshlrev_b32_e32 v86, 16, v36
	v_and_b32_e32 v87, 0xffff0000, v36
	v_lshlrev_b32_e32 v88, 16, v37
	v_and_b32_e32 v89, 0xffff0000, v37
	v_fmac_f32_e32 v82, s58, v86
	v_fmac_f32_e32 v83, s58, v87
	v_fmac_f32_e32 v84, s58, v88
	v_fmac_f32_e32 v85, s58, v89
	v_lshlrev_b32_e32 v86, 16, v28
	v_and_b32_e32 v87, 0xffff0000, v28
	v_lshlrev_b32_e32 v88, 16, v29
	v_and_b32_e32 v89, 0xffff0000, v29
	v_fma_f32 v82, -v86, s54, v82
	v_fma_f32 v83, -v87, s54, v83
	v_fma_f32 v84, -v88, s54, v84
	v_fma_f32 v85, -v89, s54, v85
	s_cmp_lg_u32 s87, 0
	s_mov_b32 s84, 0x3e800000
	s_cselect_b32 s84, 0x3eaaaaab, s84
	v_lshlrev_b32_e32 v86, 16, v34
	v_and_b32_e32 v87, 0xffff0000, v34
	v_lshlrev_b32_e32 v88, 16, v35
	v_and_b32_e32 v89, 0xffff0000, v35
	v_mul_f32_e32 v86, s57, v86
	v_mul_f32_e32 v87, s57, v87
	v_mul_f32_e32 v88, s57, v88
	v_mul_f32_e32 v89, s57, v89
	v_fma_f32 v90, v82, s84, -v86
	v_fma_f32 v91, v83, s84, -v87
	v_fma_f32 v92, v84, s84, -v88
	v_fma_f32 v93, v85, s84, -v89
	v_cvt_pk_bf16_f32 v94, v90, v91
	v_cvt_pk_bf16_f32 v95, v92, v93
	global_store_dwordx2 v62, v[94:95], s[2:3]
	s_branch .Lpool_next
.Lpool_g2:
	s_sub_i32 s84, s83, 4
	v_add_u32_e32 v64, s84, v205
	s_cmp_lg_u32 s86, 0
	s_cselect_b32 s85, 4, 0
	s_cmp_lg_u32 s87, 0
	s_cselect_b32 s101, 20, 23
	v_cmp_le_u32_e64 s[4:5], s85, v205
	v_cmp_gt_u32_e32 vcc, s101, v205
	s_and_b64 vcc, vcc, s[4:5]
	v_mov_b32_e32 v65, s83
	v_cndmask_b32_e32 v64, v65, v64, vcc
	v_lshlrev_b32_e32 v64, 6, v64
	s_add_u32 s2, s80, 0x13648000
	s_addc_u32 s3, s81, 0
	global_load_dwordx4 v[66:69], v64, s[2:3]
	global_load_dwordx4 v[70:73], v64, s[2:3] offset:16
	global_load_dwordx4 v[74:77], v64, s[2:3] offset:32
	global_load_dwordx4 v[78:81], v64, s[2:3] offset:48
	s_add_u32 s2, s80, 0x87c8400
	s_addc_u32 s3, s81, 0
	s_lshl_b32 s85, s83, 11
	s_add_u32 s4, s2, s85
	s_addc_u32 s5, s3, 0
	s_sub_u32 s2, s4, 0x2000
	s_subb_u32 s3, s5, 0
	s_cmp_lg_u32 s86, 0
	s_cselect_b64 s[84:85], s[4:5], s[2:3]
	global_load_dwordx2 v[0:1], v62, s[84:85]
	s_add_u32 s2, s2, 0x800
	s_addc_u32 s3, s3, 0
	s_cmp_lg_u32 s86, 0
	s_cselect_b64 s[84:85], s[4:5], s[2:3]
	global_load_dwordx2 v[2:3], v62, s[84:85]
	s_add_u32 s2, s2, 0x800
	s_addc_u32 s3, s3, 0
	s_cmp_lg_u32 s86, 0
	s_cselect_b64 s[84:85], s[4:5], s[2:3]
	global_load_dwordx2 v[4:5], v62, s[84:85]
	s_add_u32 s2, s2, 0x800
	s_addc_u32 s3, s3, 0
	s_cmp_lg_u32 s86, 0
	s_cselect_b64 s[84:85], s[4:5], s[2:3]
	global_load_dwordx2 v[6:7], v62, s[84:85]
	s_add_u32 s2, s2, 0x800
	s_addc_u32 s3, s3, 0
	global_load_dwordx2 v[8:9], v62, s[2:3]
	s_add_u32 s2, s2, 0x800
	s_addc_u32 s3, s3, 0
	global_load_dwordx2 v[10:11], v62, s[2:3]
	s_add_u32 s2, s2, 0x800
	s_addc_u32 s3, s3, 0
	global_load_dwordx2 v[12:13], v62, s[2:3]
	s_add_u32 s2, s2, 0x800
	s_addc_u32 s3, s3, 0
	global_load_dwordx2 v[14:15], v62, s[2:3]
	s_add_u32 s2, s2, 0x800
	s_addc_u32 s3, s3, 0
	global_load_dwordx2 v[16:17], v62, s[2:3]
	s_add_u32 s2, s2, 0x800
	s_addc_u32 s3, s3, 0
	global_load_dwordx2 v[18:19], v62, s[2:3]
	s_add_u32 s2, s2, 0x800
	s_addc_u32 s3, s3, 0
	global_load_dwordx2 v[20:21], v62, s[2:3]
	s_add_u32 s2, s2, 0x800
	s_addc_u32 s3, s3, 0
	global_load_dwordx2 v[22:23], v62, s[2:3]
	s_add_u32 s2, s2, 0x800
	s_addc_u32 s3, s3, 0
	global_load_dwordx2 v[24:25], v62, s[2:3]
	s_add_u32 s2, s2, 0x800
	s_addc_u32 s3, s3, 0
	global_load_dwordx2 v[26:27], v62, s[2:3]
	s_add_u32 s2, s2, 0x800
	s_addc_u32 s3, s3, 0
	global_load_dwordx2 v[28:29], v62, s[2:3]
	s_add_u32 s2, s2, 0x800
	s_addc_u32 s3, s3, 0
	global_load_dwordx2 v[30:31], v62, s[2:3]
	s_add_u32 s2, s2, 0x800
	s_addc_u32 s3, s3, 0
	global_load_dwordx2 v[32:33], v62, s[2:3]
	s_add_u32 s2, s2, 0x800
	s_addc_u32 s3, s3, 0
	global_load_dwordx2 v[34:35], v62, s[2:3]
	s_add_u32 s2, s2, 0x800
	s_addc_u32 s3, s3, 0
	global_load_dwordx2 v[36:37], v62, s[2:3]
	s_add_u32 s2, s2, 0x800
	s_addc_u32 s3, s3, 0
	global_load_dwordx2 v[38:39], v62, s[2:3]
	s_add_u32 s2, s2, 0x800
	s_addc_u32 s3, s3, 0
	s_cmp_lg_u32 s87, 0
	s_cselect_b64 s[84:85], s[4:5], s[2:3]
	global_load_dwordx2 v[40:41], v62, s[84:85]
	s_add_u32 s2, s2, 0x800
	s_addc_u32 s3, s3, 0
	s_cmp_lg_u32 s87, 0
	s_cselect_b64 s[84:85], s[4:5], s[2:3]
	global_load_dwordx2 v[42:43], v62, s[84:85]
	s_add_u32 s2, s2, 0x800
	s_addc_u32 s3, s3, 0
	s_cmp_lg_u32 s87, 0
	s_cselect_b64 s[84:85], s[4:5], s[2:3]
	global_load_dwordx2 v[44:45], v62, s[84:85]
	s_waitcnt vmcnt(23)
	v_add_f32_e32 v66, v66, v67
	v_add_f32_e32 v68, v68, v69
	v_add_f32_e32 v70, v70, v71
	v_add_f32_e32 v72, v72, v73
	v_add_f32_e32 v74, v74, v75
	v_add_f32_e32 v76, v76, v77
	v_add_f32_e32 v78, v78, v79
	v_add_f32_e32 v80, v80, v81
	v_add_f32_e32 v66, v66, v68
	v_add_f32_e32 v70, v70, v72
	v_add_f32_e32 v74, v74, v76
	v_add_f32_e32 v78, v78, v80
	v_add_f32_e32 v66, v66, v70
	v_add_f32_e32 v74, v74, v78
	v_add_f32_e32 v66, v66, v74
	v_fmamk_f32 v66, v66, 0x3a800000, v207
	v_rsq_f32_e32 v66, v66
	s_nop 0
	v_cndmask_b32_e32 v63, 0, v66, vcc
	s_nop 1
	v_readlane_b32 s40, v63, 0
	v_readlane_b32 s41, v63, 1
	v_readlane_b32 s42, v63, 2
	v_readlane_b32 s43, v63, 3
	v_readlane_b32 s44, v63, 4
	v_readlane_b32 s45, v63, 5
	v_readlane_b32 s46, v63, 6
	v_readlane_b32 s47, v63, 7
	v_readlane_b32 s48, v63, 8
	v_readlane_b32 s49, v63, 9
	v_readlane_b32 s50, v63, 10
	v_readlane_b32 s51, v63, 11
	v_readlane_b32 s52, v63, 12
	v_readlane_b32 s53, v63, 13
	v_readlane_b32 s54, v63, 14
	v_readlane_b32 s55, v63, 15
	v_readlane_b32 s56, v63, 16
	v_readlane_b32 s57, v63, 17
	v_readlane_b32 s58, v63, 18
	v_readlane_b32 s59, v63, 19
	v_readlane_b32 s60, v63, 20
	v_readlane_b32 s61, v63, 21
	v_readlane_b32 s62, v63, 22
	s_add_u32 s2, s80, 0x9fc8400
	s_addc_u32 s3, s81, 0
	s_lshl_b32 s85, s83, 11
	s_add_u32 s2, s2, s85
	s_addc_u32 s3, s3, 0
	s_waitcnt vmcnt(15)
	v_lshlrev_b32_e32 v86, 16, v0
	v_and_b32_e32 v87, 0xffff0000, v0
	v_lshlrev_b32_e32 v88, 16, v1
	v_and_b32_e32 v89, 0xffff0000, v1
	v_mul_f32_e32 v82, s40, v86
	v_mul_f32_e32 v83, s40, v87
	v_mul_f32_e32 v84, s40, v88
	v_mul_f32_e32 v85, s40, v89
	v_lshlrev_b32_e32 v86, 16, v2
	v_and_b32_e32 v87, 0xffff0000, v2
	v_lshlrev_b32_e32 v88, 16, v3
	v_and_b32_e32 v89, 0xffff0000, v3
	v_fmac_f32_e32 v82, s41, v86
	v_fmac_f32_e32 v83, s41, v87
	v_fmac_f32_e32 v84, s41, v88
	v_fmac_f32_e32 v85, s41, v89
	v_lshlrev_b32_e32 v86, 16, v4
	v_and_b32_e32 v87, 0xffff0000, v4
	v_lshlrev_b32_e32 v88, 16, v5
	v_and_b32_e32 v89, 0xffff0000, v5
	v_fmac_f32_e32 v82, s42, v86
	v_fmac_f32_e32 v83, s42, v87
	v_fmac_f32_e32 v84, s42, v88
	v_fmac_f32_e32 v85, s42, v89
	v_lshlrev_b32_e32 v86, 16, v6
	v_and_b32_e32 v87, 0xffff0000, v6
	v_lshlrev_b32_e32 v88, 16, v7
	v_and_b32_e32 v89, 0xffff0000, v7
	v_fmac_f32_e32 v82, s43, v86
	v_fmac_f32_e32 v83, s43, v87
	v_fmac_f32_e32 v84, s43, v88
	v_fmac_f32_e32 v85, s43, v89
	v_lshlrev_b32_e32 v86, 16, v8
	v_and_b32_e32 v87, 0xffff0000, v8
	v_lshlrev_b32_e32 v88, 16, v9
	v_and_b32_e32 v89, 0xffff0000, v9
	v_fmac_f32_e32 v82, s44, v86
	v_fmac_f32_e32 v83, s44, v87
	v_fmac_f32_e32 v84, s44, v88
	v_fmac_f32_e32 v85, s44, v89
	v_lshlrev_b32_e32 v86, 16, v10
	v_and_b32_e32 v87, 0xffff0000, v10
	v_lshlrev_b32_e32 v88, 16, v11
	v_and_b32_e32 v89, 0xffff0000, v11
	v_fmac_f32_e32 v82, s45, v86
	v_fmac_f32_e32 v83, s45, v87
	v_fmac_f32_e32 v84, s45, v88
	v_fmac_f32_e32 v85, s45, v89
	v_lshlrev_b32_e32 v86, 16, v12
	v_and_b32_e32 v87, 0xffff0000, v12
	v_lshlrev_b32_e32 v88, 16, v13
	v_and_b32_e32 v89, 0xffff0000, v13
	v_fmac_f32_e32 v82, s46, v86
	v_fmac_f32_e32 v83, s46, v87
	v_fmac_f32_e32 v84, s46, v88
	v_fmac_f32_e32 v85, s46, v89
	v_lshlrev_b32_e32 v86, 16, v14
	v_and_b32_e32 v87, 0xffff0000, v14
	v_lshlrev_b32_e32 v88, 16, v15
	v_and_b32_e32 v89, 0xffff0000, v15
	v_fmac_f32_e32 v82, s47, v86
	v_fmac_f32_e32 v83, s47, v87
	v_fmac_f32_e32 v84, s47, v88
	v_fmac_f32_e32 v85, s47, v89
	s_cmp_lg_u32 s86, 0
	s_mov_b32 s84, 0x3e000000
	s_cselect_b32 s84, 0x3e800000, s84
	v_lshlrev_b32_e32 v86, 16, v8
	v_and_b32_e32 v87, 0xffff0000, v8
	v_lshlrev_b32_e32 v88, 16, v9
	v_and_b32_e32 v89, 0xffff0000, v9
	v_mul_f32_e32 v86, s44, v86
	v_mul_f32_e32 v87, s44, v87
	v_mul_f32_e32 v88, s44, v88
	v_mul_f32_e32 v89, s44, v89
	v_fma_f32 v90, v82, s84, -v86
	v_fma_f32 v91, v83, s84, -v87
	v_fma_f32 v92, v84, s84, -v88
	v_fma_f32 v93, v85, s84, -v89
	v_cvt_pk_bf16_f32 v94, v90, v91
	v_cvt_pk_bf16_f32 v95, v92, v93
	global_store_dwordx2 v62, v[94:95], s[2:3]
	s_add_u32 s2, s2, 0x800
	s_addc_u32 s3, s3, 0
	s_waitcnt vmcnt(15)
	v_lshlrev_b32_e32 v86, 16, v16
	v_and_b32_e32 v87, 0xffff0000, v16
	v_lshlrev_b32_e32 v88, 16, v17
	v_and_b32_e32 v89, 0xffff0000, v17
	v_fmac_f32_e32 v82, s48, v86
	v_fmac_f32_e32 v83, s48, v87
	v_fmac_f32_e32 v84, s48, v88
	v_fmac_f32_e32 v85, s48, v89
	v_lshlrev_b32_e32 v86, 16, v0
	v_and_b32_e32 v87, 0xffff0000, v0
	v_lshlrev_b32_e32 v88, 16, v1
	v_and_b32_e32 v89, 0xffff0000, v1
	v_fma_f32 v82, -v86, s40, v82
	v_fma_f32 v83, -v87, s40, v83
	v_fma_f32 v84, -v88, s40, v84
	v_fma_f32 v85, -v89, s40, v85
	s_cmp_lg_u32 s86, 0
	s_mov_b32 s84, 0x3e000000
	s_cselect_b32 s84, 0x3e4ccccd, s84
	v_lshlrev_b32_e32 v86, 16, v10
	v_and_b32_e32 v87, 0xffff0000, v10
	v_lshlrev_b32_e32 v88, 16, v11
	v_and_b32_e32 v89, 0xffff0000, v11
	v_mul_f32_e32 v86, s45, v86
	v_mul_f32_e32 v87, s45, v87
	v_mul_f32_e32 v88, s45, v88
	v_mul_f32_e32 v89, s45, v89
	v_fma_f32 v90, v82, s84, -v86
	v_fma_f32 v91, v83, s84, -v87
	v_fma_f32 v92, v84, s84, -v88
	v_fma_f32 v93, v85, s84, -v89
	v_cvt_pk_bf16_f32 v94, v90, v91
	v_cvt_pk_bf16_f32 v95, v92, v93
	global_store_dwordx2 v62, v[94:95], s[2:3]
	s_add_u32 s2, s2, 0x800
	s_addc_u32 s3, s3, 0
	s_waitcnt vmcnt(15)
	v_lshlrev_b32_e32 v86, 16, v18
	v_and_b32_e32 v87, 0xffff0000, v18
	v_lshlrev_b32_e32 v88, 16, v19
	v_and_b32_e32 v89, 0xffff0000, v19
	v_fmac_f32_e32 v82, s49, v86
	v_fmac_f32_e32 v83, s49, v87
	v_fmac_f32_e32 v84, s49, v88
	v_fmac_f32_e32 v85, s49, v89
	v_lshlrev_b32_e32 v86, 16, v2
	v_and_b32_e32 v87, 0xffff0000, v2
	v_lshlrev_b32_e32 v88, 16, v3
	v_and_b32_e32 v89, 0xffff0000, v3
	v_fma_f32 v82, -v86, s41, v82
	v_fma_f32 v83, -v87, s41, v83
	v_fma_f32 v84, -v88, s41, v84
	v_fma_f32 v85, -v89, s41, v85
	s_cmp_lg_u32 s86, 0
	s_mov_b32 s84, 0x3e000000
	s_cselect_b32 s84, 0x3e2aaaab, s84
	v_lshlrev_b32_e32 v86, 16, v12
	v_and_b32_e32 v87, 0xffff0000, v12
	v_lshlrev_b32_e32 v88, 16, v13
	v_and_b32_e32 v89, 0xffff0000, v13
	v_mul_f32_e32 v86, s46, v86
	v_mul_f32_e32 v87, s46, v87
	v_mul_f32_e32 v88, s46, v88
	v_mul_f32_e32 v89, s46, v89
	v_fma_f32 v90, v82, s84, -v86
	v_fma_f32 v91, v83, s84, -v87
	v_fma_f32 v92, v84, s84, -v88
	v_fma_f32 v93, v85, s84, -v89
	v_cvt_pk_bf16_f32 v94, v90, v91
	v_cvt_pk_bf16_f32 v95, v92, v93
	global_store_dwordx2 v62, v[94:95], s[2:3]
	s_add_u32 s2, s2, 0x800
	s_addc_u32 s3, s3, 0
	s_waitcnt vmcnt(15)
	v_lshlrev_b32_e32 v86, 16, v20
	v_and_b32_e32 v87, 0xffff0000, v20
	v_lshlrev_b32_e32 v88, 16, v21
	v_and_b32_e32 v89, 0xffff0000, v21
	v_fmac_f32_e32 v82, s50, v86
	v_fmac_f32_e32 v83, s50, v87
	v_fmac_f32_e32 v84, s50, v88
	v_fmac_f32_e32 v85, s50, v89
	v_lshlrev_b32_e32 v86, 16, v4
	v_and_b32_e32 v87, 0xffff0000, v4
	v_lshlrev_b32_e32 v88, 16, v5
	v_and_b32_e32 v89, 0xffff0000, v5
	v_fma_f32 v82, -v86, s42, v82
	v_fma_f32 v83, -v87, s42, v83
	v_fma_f32 v84, -v88, s42, v84
	v_fma_f32 v85, -v89, s42, v85
	s_cmp_lg_u32 s86, 0
	s_mov_b32 s84, 0x3e000000
	s_cselect_b32 s84, 0x3e124925, s84
	v_lshlrev_b32_e32 v86, 16, v14
	v_and_b32_e32 v87, 0xffff0000, v14
	v_lshlrev_b32_e32 v88, 16, v15
	v_and_b32_e32 v89, 0xffff0000, v15
	v_mul_f32_e32 v86, s47, v86
	v_mul_f32_e32 v87, s47, v87
	v_mul_f32_e32 v88, s47, v88
	v_mul_f32_e32 v89, s47, v89
	v_fma_f32 v90, v82, s84, -v86
	v_fma_f32 v91, v83, s84, -v87
	v_fma_f32 v92, v84, s84, -v88
	v_fma_f32 v93, v85, s84, -v89
	v_cvt_pk_bf16_f32 v94, v90, v91
	v_cvt_pk_bf16_f32 v95, v92, v93
	global_store_dwordx2 v62, v[94:95], s[2:3]
	s_add_u32 s2, s2, 0x800
	s_addc_u32 s3, s3, 0
	s_waitcnt vmcnt(15)
	v_lshlrev_b32_e32 v86, 16, v22
	v_and_b32_e32 v87, 0xffff0000, v22
	v_lshlrev_b32_e32 v88, 16, v23
	v_and_b32_e32 v89, 0xffff0000, v23
	v_fmac_f32_e32 v82, s51, v86
	v_fmac_f32_e32 v83, s51, v87
	v_fmac_f32_e32 v84, s51, v88
	v_fmac_f32_e32 v85, s51, v89
	v_lshlrev_b32_e32 v86, 16, v6
	v_and_b32_e32 v87, 0xffff0000, v6
	v_lshlrev_b32_e32 v88, 16, v7
	v_and_b32_e32 v89, 0xffff0000, v7
	v_fma_f32 v82, -v86, s43, v82
	v_fma_f32 v83, -v87, s43, v83
	v_fma_f32 v84, -v88, s43, v84
	v_fma_f32 v85, -v89, s43, v85
	s_mov_b32 s84, 0x3e000000
	v_lshlrev_b32_e32 v86, 16, v16
	v_and_b32_e32 v87, 0xffff0000, v16
	v_lshlrev_b32_e32 v88, 16, v17
	v_and_b32_e32 v89, 0xffff0000, v17
	v_mul_f32_e32 v86, s48, v86
	v_mul_f32_e32 v87, s48, v87
	v_mul_f32_e32 v88, s48, v88
	v_mul_f32_e32 v89, s48, v89
	v_fma_f32 v90, v82, s84, -v86
	v_fma_f32 v91, v83, s84, -v87
	v_fma_f32 v92, v84, s84, -v88
	v_fma_f32 v93, v85, s84, -v89
	v_cvt_pk_bf16_f32 v94, v90, v91
	v_cvt_pk_bf16_f32 v95, v92, v93
	global_store_dwordx2 v62, v[94:95], s[2:3]
	s_add_u32 s2, s2, 0x800
	s_addc_u32 s3, s3, 0
	s_waitcnt vmcnt(15)
	v_lshlrev_b32_e32 v86, 16, v24
	v_and_b32_e32 v87, 0xffff0000, v24
	v_lshlrev_b32_e32 v88, 16, v25
	v_and_b32_e32 v89, 0xffff0000, v25
	v_fmac_f32_e32 v82, s52, v86
	v_fmac_f32_e32 v83, s52, v87
	v_fmac_f32_e32 v84, s52, v88
	v_fmac_f32_e32 v85, s52, v89
	v_lshlrev_b32_e32 v86, 16, v8
	v_and_b32_e32 v87, 0xffff0000, v8
	v_lshlrev_b32_e32 v88, 16, v9
	v_and_b32_e32 v89, 0xffff0000, v9
	v_fma_f32 v82, -v86, s44, v82
	v_fma_f32 v83, -v87, s44, v83
	v_fma_f32 v84, -v88, s44, v84
	v_fma_f32 v85, -v89, s44, v85
	s_mov_b32 s84, 0x3e000000
	v_lshlrev_b32_e32 v86, 16, v18
	v_and_b32_e32 v87, 0xffff0000, v18
	v_lshlrev_b32_e32 v88, 16, v19
	v_and_b32_e32 v89, 0xffff0000, v19
	v_mul_f32_e32 v86, s49, v86
	v_mul_f32_e32 v87, s49, v87
	v_mul_f32_e32 v88, s49, v88
	v_mul_f32_e32 v89, s49, v89
	v_fma_f32 v90, v82, s84, -v86
	v_fma_f32 v91, v83, s84, -v87
	v_fma_f32 v92, v84, s84, -v88
	v_fma_f32 v93, v85, s84, -v89
	v_cvt_pk_bf16_f32 v94, v90, v91
	v_cvt_pk_bf16_f32 v95, v92, v93
	global_store_dwordx2 v62, v[94:95], s[2:3]
	s_add_u32 s2, s2, 0x800
	s_addc_u32 s3, s3, 0
	s_waitcnt vmcnt(15)
	v_lshlrev_b32_e32 v86, 16, v26
	v_and_b32_e32 v87, 0xffff0000, v26
	v_lshlrev_b32_e32 v88, 16, v27
	v_and_b32_e32 v89, 0xffff0000, v27
	v_fmac_f32_e32 v82, s53, v86
	v_fmac_f32_e32 v83, s53, v87
	v_fmac_f32_e32 v84, s53, v88
	v_fmac_f32_e32 v85, s53, v89
	v_lshlrev_b32_e32 v86, 16, v10
	v_and_b32_e32 v87, 0xffff0000, v10
	v_lshlrev_b32_e32 v88, 16, v11
	v_and_b32_e32 v89, 0xffff0000, v11
	v_fma_f32 v82, -v86, s45, v82
	v_fma_f32 v83, -v87, s45, v83
	v_fma_f32 v84, -v88, s45, v84
	v_fma_f32 v85, -v89, s45, v85
	s_mov_b32 s84, 0x3e000000
	v_lshlrev_b32_e32 v86, 16, v20
	v_and_b32_e32 v87, 0xffff0000, v20
	v_lshlrev_b32_e32 v88, 16, v21
	v_and_b32_e32 v89, 0xffff0000, v21
	v_mul_f32_e32 v86, s50, v86
	v_mul_f32_e32 v87, s50, v87
	v_mul_f32_e32 v88, s50, v88
	v_mul_f32_e32 v89, s50, v89
	v_fma_f32 v90, v82, s84, -v86
	v_fma_f32 v91, v83, s84, -v87
	v_fma_f32 v92, v84, s84, -v88
	v_fma_f32 v93, v85, s84, -v89
	v_cvt_pk_bf16_f32 v94, v90, v91
	v_cvt_pk_bf16_f32 v95, v92, v93
	global_store_dwordx2 v62, v[94:95], s[2:3]
	s_add_u32 s2, s2, 0x800
	s_addc_u32 s3, s3, 0
	s_waitcnt vmcnt(15)
	v_lshlrev_b32_e32 v86, 16, v28
	v_and_b32_e32 v87, 0xffff0000, v28
	v_lshlrev_b32_e32 v88, 16, v29
	v_and_b32_e32 v89, 0xffff0000, v29
	v_fmac_f32_e32 v82, s54, v86
	v_fmac_f32_e32 v83, s54, v87
	v_fmac_f32_e32 v84, s54, v88
	v_fmac_f32_e32 v85, s54, v89
	v_lshlrev_b32_e32 v86, 16, v12
	v_and_b32_e32 v87, 0xffff0000, v12
	v_lshlrev_b32_e32 v88, 16, v13
	v_and_b32_e32 v89, 0xffff0000, v13
	v_fma_f32 v82, -v86, s46, v82
	v_fma_f32 v83, -v87, s46, v83
	v_fma_f32 v84, -v88, s46, v84
	v_fma_f32 v85, -v89, s46, v85
	s_mov_b32 s84, 0x3e000000
	v_lshlrev_b32_e32 v86, 16, v22
	v_and_b32_e32 v87, 0xffff0000, v22
	v_lshlrev_b32_e32 v88, 16, v23
	v_and_b32_e32 v89, 0xffff0000, v23
	v_mul_f32_e32 v86, s51, v86
	v_mul_f32_e32 v87, s51, v87
	v_mul_f32_e32 v88, s51, v88
	v_mul_f32_e32 v89, s51, v89
	v_fma_f32 v90, v82, s84, -v86
	v_fma_f32 v91, v83, s84, -v87
	v_fma_f32 v92, v84, s84, -v88
	v_fma_f32 v93, v85, s84, -v89
	v_cvt_pk_bf16_f32 v94, v90, v91
	v_cvt_pk_bf16_f32 v95, v92, v93
	global_store_dwordx2 v62, v[94:95], s[2:3]
	s_add_u32 s2, s2, 0x800
	s_addc_u32 s3, s3, 0
	s_waitcnt vmcnt(15)
	v_lshlrev_b32_e32 v86, 16, v30
	v_and_b32_e32 v87, 0xffff0000, v30
	v_lshlrev_b32_e32 v88, 16, v31
	v_and_b32_e32 v89, 0xffff0000, v31
	v_fmac_f32_e32 v82, s55, v86
	v_fmac_f32_e32 v83, s55, v87
	v_fmac_f32_e32 v84, s55, v88
	v_fmac_f32_e32 v85, s55, v89
	v_lshlrev_b32_e32 v86, 16, v14
	v_and_b32_e32 v87, 0xffff0000, v14
	v_lshlrev_b32_e32 v88, 16, v15
	v_and_b32_e32 v89, 0xffff0000, v15
	v_fma_f32 v82, -v86, s47, v82
	v_fma_f32 v83, -v87, s47, v83
	v_fma_f32 v84, -v88, s47, v84
	v_fma_f32 v85, -v89, s47, v85
	s_mov_b32 s84, 0x3e000000
	v_lshlrev_b32_e32 v86, 16, v24
	v_and_b32_e32 v87, 0xffff0000, v24
	v_lshlrev_b32_e32 v88, 16, v25
	v_and_b32_e32 v89, 0xffff0000, v25
	v_mul_f32_e32 v86, s52, v86
	v_mul_f32_e32 v87, s52, v87
	v_mul_f32_e32 v88, s52, v88
	v_mul_f32_e32 v89, s52, v89
	v_fma_f32 v90, v82, s84, -v86
	v_fma_f32 v91, v83, s84, -v87
	v_fma_f32 v92, v84, s84, -v88
	v_fma_f32 v93, v85, s84, -v89
	v_cvt_pk_bf16_f32 v94, v90, v91
	v_cvt_pk_bf16_f32 v95, v92, v93
	global_store_dwordx2 v62, v[94:95], s[2:3]
	s_add_u32 s2, s2, 0x800
	s_addc_u32 s3, s3, 0
	s_waitcnt vmcnt(15)
	v_lshlrev_b32_e32 v86, 16, v32
	v_and_b32_e32 v87, 0xffff0000, v32
	v_lshlrev_b32_e32 v88, 16, v33
	v_and_b32_e32 v89, 0xffff0000, v33
	v_fmac_f32_e32 v82, s56, v86
	v_fmac_f32_e32 v83, s56, v87
	v_fmac_f32_e32 v84, s56, v88
	v_fmac_f32_e32 v85, s56, v89
	v_lshlrev_b32_e32 v86, 16, v16
	v_and_b32_e32 v87, 0xffff0000, v16
	v_lshlrev_b32_e32 v88, 16, v17
	v_and_b32_e32 v89, 0xffff0000, v17
	v_fma_f32 v82, -v86, s48, v82
	v_fma_f32 v83, -v87, s48, v83
	v_fma_f32 v84, -v88, s48, v84
	v_fma_f32 v85, -v89, s48, v85
	s_mov_b32 s84, 0x3e000000
	v_lshlrev_b32_e32 v86, 16, v26
	v_and_b32_e32 v87, 0xffff0000, v26
	v_lshlrev_b32_e32 v88, 16, v27
	v_and_b32_e32 v89, 0xffff0000, v27
	v_mul_f32_e32 v86, s53, v86
	v_mul_f32_e32 v87, s53, v87
	v_mul_f32_e32 v88, s53, v88
	v_mul_f32_e32 v89, s53, v89
	v_fma_f32 v90, v82, s84, -v86
	v_fma_f32 v91, v83, s84, -v87
	v_fma_f32 v92, v84, s84, -v88
	v_fma_f32 v93, v85, s84, -v89
	v_cvt_pk_bf16_f32 v94, v90, v91
	v_cvt_pk_bf16_f32 v95, v92, v93
	global_store_dwordx2 v62, v[94:95], s[2:3]
	s_add_u32 s2, s2, 0x800
	s_addc_u32 s3, s3, 0
	s_waitcnt vmcnt(15)
	v_lshlrev_b32_e32 v86, 16, v34
	v_and_b32_e32 v87, 0xffff0000, v34
	v_lshlrev_b32_e32 v88, 16, v35
	v_and_b32_e32 v89, 0xffff0000, v35
	v_fmac_f32_e32 v82, s57, v86
	v_fmac_f32_e32 v83, s57, v87
	v_fmac_f32_e32 v84, s57, v88
	v_fmac_f32_e32 v85, s57, v89
	v_lshlrev_b32_e32 v86, 16, v18
	v_and_b32_e32 v87, 0xffff0000, v18
	v_lshlrev_b32_e32 v88, 16, v19
	v_and_b32_e32 v89, 0xffff0000, v19
	v_fma_f32 v82, -v86, s49, v82
	v_fma_f32 v83, -v87, s49, v83
	v_fma_f32 v84, -v88, s49, v84
	v_fma_f32 v85, -v89, s49, v85
	s_mov_b32 s84, 0x3e000000
	v_lshlrev_b32_e32 v86, 16, v28
	v_and_b32_e32 v87, 0xffff0000, v28
	v_lshlrev_b32_e32 v88, 16, v29
	v_and_b32_e32 v89, 0xffff0000, v29
	v_mul_f32_e32 v86, s54, v86
	v_mul_f32_e32 v87, s54, v87
	v_mul_f32_e32 v88, s54, v88
	v_mul_f32_e32 v89, s54, v89
	v_fma_f32 v90, v82, s84, -v86
	v_fma_f32 v91, v83, s84, -v87
	v_fma_f32 v92, v84, s84, -v88
	v_fma_f32 v93, v85, s84, -v89
	v_cvt_pk_bf16_f32 v94, v90, v91
	v_cvt_pk_bf16_f32 v95, v92, v93
	global_store_dwordx2 v62, v[94:95], s[2:3]
	s_add_u32 s2, s2, 0x800
	s_addc_u32 s3, s3, 0
	s_waitcnt vmcnt(15)
	v_lshlrev_b32_e32 v86, 16, v36
	v_and_b32_e32 v87, 0xffff0000, v36
	v_lshlrev_b32_e32 v88, 16, v37
	v_and_b32_e32 v89, 0xffff0000, v37
	v_fmac_f32_e32 v82, s58, v86
	v_fmac_f32_e32 v83, s58, v87
	v_fmac_f32_e32 v84, s58, v88
	v_fmac_f32_e32 v85, s58, v89
	v_lshlrev_b32_e32 v86, 16, v20
	v_and_b32_e32 v87, 0xffff0000, v20
	v_lshlrev_b32_e32 v88, 16, v21
	v_and_b32_e32 v89, 0xffff0000, v21
	v_fma_f32 v82, -v86, s50, v82
	v_fma_f32 v83, -v87, s50, v83
	v_fma_f32 v84, -v88, s50, v84
	v_fma_f32 v85, -v89, s50, v85
	s_mov_b32 s84, 0x3e000000
	v_lshlrev_b32_e32 v86, 16, v30
	v_and_b32_e32 v87, 0xffff0000, v30
	v_lshlrev_b32_e32 v88, 16, v31
	v_and_b32_e32 v89, 0xffff0000, v31
	v_mul_f32_e32 v86, s55, v86
	v_mul_f32_e32 v87, s55, v87
	v_mul_f32_e32 v88, s55, v88
	v_mul_f32_e32 v89, s55, v89
	v_fma_f32 v90, v82, s84, -v86
	v_fma_f32 v91, v83, s84, -v87
	v_fma_f32 v92, v84, s84, -v88
	v_fma_f32 v93, v85, s84, -v89
	v_cvt_pk_bf16_f32 v94, v90, v91
	v_cvt_pk_bf16_f32 v95, v92, v93
	global_store_dwordx2 v62, v[94:95], s[2:3]
	s_add_u32 s2, s2, 0x800
	s_addc_u32 s3, s3, 0
	s_waitcnt vmcnt(15)
	v_lshlrev_b32_e32 v86, 16, v38
	v_and_b32_e32 v87, 0xffff0000, v38
	v_lshlrev_b32_e32 v88, 16, v39
	v_and_b32_e32 v89, 0xffff0000, v39
	v_fmac_f32_e32 v82, s59, v86
	v_fmac_f32_e32 v83, s59, v87
	v_fmac_f32_e32 v84, s59, v88
	v_fmac_f32_e32 v85, s59, v89
	v_lshlrev_b32_e32 v86, 16, v22
	v_and_b32_e32 v87, 0xffff0000, v22
	v_lshlrev_b32_e32 v88, 16, v23
	v_and_b32_e32 v89, 0xffff0000, v23
	v_fma_f32 v82, -v86, s51, v82
	v_fma_f32 v83, -v87, s51, v83
	v_fma_f32 v84, -v88, s51, v84
	v_fma_f32 v85, -v89, s51, v85
	s_mov_b32 s84, 0x3e000000
	v_lshlrev_b32_e32 v86, 16, v32
	v_and_b32_e32 v87, 0xffff0000, v32
	v_lshlrev_b32_e32 v88, 16, v33
	v_and_b32_e32 v89, 0xffff0000, v33
	v_mul_f32_e32 v86, s56, v86
	v_mul_f32_e32 v87, s56, v87
	v_mul_f32_e32 v88, s56, v88
	v_mul_f32_e32 v89, s56, v89
	v_fma_f32 v90, v82, s84, -v86
	v_fma_f32 v91, v83, s84, -v87
	v_fma_f32 v92, v84, s84, -v88
	v_fma_f32 v93, v85, s84, -v89
	v_cvt_pk_bf16_f32 v94, v90, v91
	v_cvt_pk_bf16_f32 v95, v92, v93
	global_store_dwordx2 v62, v[94:95], s[2:3]
	s_add_u32 s2, s2, 0x800
	s_addc_u32 s3, s3, 0
	s_waitcnt vmcnt(15)
	v_lshlrev_b32_e32 v86, 16, v40
	v_and_b32_e32 v87, 0xffff0000, v40
	v_lshlrev_b32_e32 v88, 16, v41
	v_and_b32_e32 v89, 0xffff0000, v41
	v_fmac_f32_e32 v82, s60, v86
	v_fmac_f32_e32 v83, s60, v87
	v_fmac_f32_e32 v84, s60, v88
	v_fmac_f32_e32 v85, s60, v89
	v_lshlrev_b32_e32 v86, 16, v24
	v_and_b32_e32 v87, 0xffff0000, v24
	v_lshlrev_b32_e32 v88, 16, v25
	v_and_b32_e32 v89, 0xffff0000, v25
	v_fma_f32 v82, -v86, s52, v82
	v_fma_f32 v83, -v87, s52, v83
	v_fma_f32 v84, -v88, s52, v84
	v_fma_f32 v85, -v89, s52, v85
	s_cmp_lg_u32 s87, 0
	s_mov_b32 s84, 0x3e000000
	s_cselect_b32 s84, 0x3e124925, s84
	v_lshlrev_b32_e32 v86, 16, v34
	v_and_b32_e32 v87, 0xffff0000, v34
	v_lshlrev_b32_e32 v88, 16, v35
	v_and_b32_e32 v89, 0xffff0000, v35
	v_mul_f32_e32 v86, s57, v86
	v_mul_f32_e32 v87, s57, v87
	v_mul_f32_e32 v88, s57, v88
	v_mul_f32_e32 v89, s57, v89
	v_fma_f32 v90, v82, s84, -v86
	v_fma_f32 v91, v83, s84, -v87
	v_fma_f32 v92, v84, s84, -v88
	v_fma_f32 v93, v85, s84, -v89
	v_cvt_pk_bf16_f32 v94, v90, v91
	v_cvt_pk_bf16_f32 v95, v92, v93
	global_store_dwordx2 v62, v[94:95], s[2:3]
	s_add_u32 s2, s2, 0x800
	s_addc_u32 s3, s3, 0
	s_waitcnt vmcnt(15)
	v_lshlrev_b32_e32 v86, 16, v42
	v_and_b32_e32 v87, 0xffff0000, v42
	v_lshlrev_b32_e32 v88, 16, v43
	v_and_b32_e32 v89, 0xffff0000, v43
	v_fmac_f32_e32 v82, s61, v86
	v_fmac_f32_e32 v83, s61, v87
	v_fmac_f32_e32 v84, s61, v88
	v_fmac_f32_e32 v85, s61, v89
	v_lshlrev_b32_e32 v86, 16, v26
	v_and_b32_e32 v87, 0xffff0000, v26
	v_lshlrev_b32_e32 v88, 16, v27
	v_and_b32_e32 v89, 0xffff0000, v27
	v_fma_f32 v82, -v86, s53, v82
	v_fma_f32 v83, -v87, s53, v83
	v_fma_f32 v84, -v88, s53, v84
	v_fma_f32 v85, -v89, s53, v85
	s_cmp_lg_u32 s87, 0
	s_mov_b32 s84, 0x3e000000
	s_cselect_b32 s84, 0x3e2aaaab, s84
	v_lshlrev_b32_e32 v86, 16, v36
	v_and_b32_e32 v87, 0xffff0000, v36
	v_lshlrev_b32_e32 v88, 16, v37
	v_and_b32_e32 v89, 0xffff0000, v37
	v_mul_f32_e32 v86, s58, v86
	v_mul_f32_e32 v87, s58, v87
	v_mul_f32_e32 v88, s58, v88
	v_mul_f32_e32 v89, s58, v89
	v_fma_f32 v90, v82, s84, -v86
	v_fma_f32 v91, v83, s84, -v87
	v_fma_f32 v92, v84, s84, -v88
	v_fma_f32 v93, v85, s84, -v89
	v_cvt_pk_bf16_f32 v94, v90, v91
	v_cvt_pk_bf16_f32 v95, v92, v93
	global_store_dwordx2 v62, v[94:95], s[2:3]
	s_add_u32 s2, s2, 0x800
	s_addc_u32 s3, s3, 0
	s_waitcnt vmcnt(15)
	v_lshlrev_b32_e32 v86, 16, v44
	v_and_b32_e32 v87, 0xffff0000, v44
	v_lshlrev_b32_e32 v88, 16, v45
	v_and_b32_e32 v89, 0xffff0000, v45
	v_fmac_f32_e32 v82, s62, v86
	v_fmac_f32_e32 v83, s62, v87
	v_fmac_f32_e32 v84, s62, v88
	v_fmac_f32_e32 v85, s62, v89
	v_lshlrev_b32_e32 v86, 16, v28
	v_and_b32_e32 v87, 0xffff0000, v28
	v_lshlrev_b32_e32 v88, 16, v29
	v_and_b32_e32 v89, 0xffff0000, v29
	v_fma_f32 v82, -v86, s54, v82
	v_fma_f32 v83, -v87, s54, v83
	v_fma_f32 v84, -v88, s54, v84
	v_fma_f32 v85, -v89, s54, v85
	s_cmp_lg_u32 s87, 0
	s_mov_b32 s84, 0x3e000000
	s_cselect_b32 s84, 0x3e4ccccd, s84
	v_lshlrev_b32_e32 v86, 16, v38
	v_and_b32_e32 v87, 0xffff0000, v38
	v_lshlrev_b32_e32 v88, 16, v39
	v_and_b32_e32 v89, 0xffff0000, v39
	v_mul_f32_e32 v86, s59, v86
	v_mul_f32_e32 v87, s59, v87
	v_mul_f32_e32 v88, s59, v88
	v_mul_f32_e32 v89, s59, v89
	v_fma_f32 v90, v82, s84, -v86
	v_fma_f32 v91, v83, s84, -v87
	v_fma_f32 v92, v84, s84, -v88
	v_fma_f32 v93, v85, s84, -v89
	v_cvt_pk_bf16_f32 v94, v90, v91
	v_cvt_pk_bf16_f32 v95, v92, v93
	global_store_dwordx2 v62, v[94:95], s[2:3]
	s_branch .Lpool_next
.Lpool_g3:
	s_sub_i32 s84, s83, 8
	v_add_u32_e32 v64, s84, v205
	s_cmp_lg_u32 s86, 0
	s_cselect_b32 s85, 8, 0
	s_cmp_lg_u32 s87, 0
	s_cselect_b32 s101, 24, 31
	v_cmp_le_u32_e64 s[4:5], s85, v205
	v_cmp_gt_u32_e32 vcc, s101, v205
	s_and_b64 vcc, vcc, s[4:5]
	v_mov_b32_e32 v65, s83
	v_cndmask_b32_e32 v64, v65, v64, vcc
	v_lshlrev_b32_e32 v64, 6, v64
	s_add_u32 s2, s80, 0x13648000
	s_addc_u32 s3, s81, 0
	global_load_dwordx4 v[66:69], v64, s[2:3]
	global_load_dwordx4 v[70:73], v64, s[2:3] offset:16
	global_load_dwordx4 v[74:77], v64, s[2:3] offset:32
	global_load_dwordx4 v[78:81], v64, s[2:3] offset:48
	s_add_u32 s2, s80, 0x87c8600
	s_addc_u32 s3, s81, 0
	s_lshl_b32 s85, s83, 11
	s_add_u32 s4, s2, s85
	s_addc_u32 s5, s3, 0
	s_sub_u32 s2, s4, 0x4000
	s_subb_u32 s3, s5, 0
	s_cmp_lg_u32 s86, 0
	s_cselect_b64 s[84:85], s[4:5], s[2:3]
	global_load_dwordx2 v[0:1], v62, s[84:85]
	s_add_u32 s2, s2, 0x800
	s_addc_u32 s3, s3, 0
	s_cmp_lg_u32 s86, 0
	s_cselect_b64 s[84:85], s[4:5], s[2:3]
	global_load_dwordx2 v[2:3], v62, s[84:85]
	s_add_u32 s2, s2, 0x800
	s_addc_u32 s3, s3, 0
	s_cmp_lg_u32 s86, 0
	s_cselect_b64 s[84:85], s[4:5], s[2:3]
	global_load_dwordx2 v[4:5], v62, s[84:85]
	s_add_u32 s2, s2, 0x800
	s_addc_u32 s3, s3, 0
	s_cmp_lg_u32 s86, 0
	s_cselect_b64 s[84:85], s[4:5], s[2:3]
	global_load_dwordx2 v[6:7], v62, s[84:85]
	s_add_u32 s2, s2, 0x800
	s_addc_u32 s3, s3, 0
	s_cmp_lg_u32 s86, 0
	s_cselect_b64 s[84:85], s[4:5], s[2:3]
	global_load_dwordx2 v[8:9], v62, s[84:85]
	s_add_u32 s2, s2, 0x800
	s_addc_u32 s3, s3, 0
	s_cmp_lg_u32 s86, 0
	s_cselect_b64 s[84:85], s[4:5], s[2:3]
	global_load_dwordx2 v[10:11], v62, s[84:85]
	s_add_u32 s2, s2, 0x800
	s_addc_u32 s3, s3, 0
	s_cmp_lg_u32 s86, 0
	s_cselect_b64 s[84:85], s[4:5], s[2:3]
	global_load_dwordx2 v[12:13], v62, s[84:85]
	s_add_u32 s2, s2, 0x800
	s_addc_u32 s3, s3, 0
	s_cmp_lg_u32 s86, 0
	s_cselect_b64 s[84:85], s[4:5], s[2:3]
	global_load_dwordx2 v[14:15], v62, s[84:85]
	s_add_u32 s2, s2, 0x800
	s_addc_u32 s3, s3, 0
	global_load_dwordx2 v[16:17], v62, s[2:3]
	s_add_u32 s2, s2, 0x800
	s_addc_u32 s3, s3, 0
	global_load_dwordx2 v[18:19], v62, s[2:3]
	s_add_u32 s2, s2, 0x800
	s_addc_u32 s3, s3, 0
	global_load_dwordx2 v[20:21], v62, s[2:3]
	s_add_u32 s2, s2, 0x800
	s_addc_u32 s3, s3, 0
	global_load_dwordx2 v[22:23], v62, s[2:3]
	s_add_u32 s2, s2, 0x800
	s_addc_u32 s3, s3, 0
	global_load_dwordx2 v[24:25], v62, s[2:3]
	s_add_u32 s2, s2, 0x800
	s_addc_u32 s3, s3, 0
	global_load_dwordx2 v[26:27], v62, s[2:3]
	s_add_u32 s2, s2, 0x800
	s_addc_u32 s3, s3, 0
	global_load_dwordx2 v[28:29], v62, s[2:3]
	s_add_u32 s2, s2, 0x800
	s_addc_u32 s3, s3, 0
	global_load_dwordx2 v[30:31], v62, s[2:3]
	s_add_u32 s2, s2, 0x800
	s_addc_u32 s3, s3, 0
	global_load_dwordx2 v[32:33], v62, s[2:3]
	s_add_u32 s2, s2, 0x800
	s_addc_u32 s3, s3, 0
	global_load_dwordx2 v[34:35], v62, s[2:3]
	s_add_u32 s2, s2, 0x800
	s_addc_u32 s3, s3, 0
	global_load_dwordx2 v[36:37], v62, s[2:3]
	s_add_u32 s2, s2, 0x800
	s_addc_u32 s3, s3, 0
	global_load_dwordx2 v[38:39], v62, s[2:3]
	s_add_u32 s2, s2, 0x800
	s_addc_u32 s3, s3, 0
	global_load_dwordx2 v[40:41], v62, s[2:3]
	s_add_u32 s2, s2, 0x800
	s_addc_u32 s3, s3, 0
	global_load_dwordx2 v[42:43], v62, s[2:3]
	s_add_u32 s2, s2, 0x800
	s_addc_u32 s3, s3, 0
	global_load_dwordx2 v[44:45], v62, s[2:3]
	s_add_u32 s2, s2, 0x800
	s_addc_u32 s3, s3, 0
	global_load_dwordx2 v[46:47], v62, s[2:3]
	s_add_u32 s2, s2, 0x800
	s_addc_u32 s3, s3, 0
	s_cmp_lg_u32 s87, 0
	s_cselect_b64 s[84:85], s[4:5], s[2:3]
	global_load_dwordx2 v[48:49], v62, s[84:85]
	s_add_u32 s2, s2, 0x800
	s_addc_u32 s3, s3, 0
	s_cmp_lg_u32 s87, 0
	s_cselect_b64 s[84:85], s[4:5], s[2:3]
	global_load_dwordx2 v[50:51], v62, s[84:85]
	s_add_u32 s2, s2, 0x800
	s_addc_u32 s3, s3, 0
	s_cmp_lg_u32 s87, 0
	s_cselect_b64 s[84:85], s[4:5], s[2:3]
	global_load_dwordx2 v[52:53], v62, s[84:85]
	s_add_u32 s2, s2, 0x800
	s_addc_u32 s3, s3, 0
	s_cmp_lg_u32 s87, 0
	s_cselect_b64 s[84:85], s[4:5], s[2:3]
	global_load_dwordx2 v[54:55], v62, s[84:85]
	s_add_u32 s2, s2, 0x800
	s_addc_u32 s3, s3, 0
	s_cmp_lg_u32 s87, 0
	s_cselect_b64 s[84:85], s[4:5], s[2:3]
	global_load_dwordx2 v[56:57], v62, s[84:85]
	s_add_u32 s2, s2, 0x800
	s_addc_u32 s3, s3, 0
	s_cmp_lg_u32 s87, 0
	s_cselect_b64 s[84:85], s[4:5], s[2:3]
	global_load_dwordx2 v[58:59], v62, s[84:85]
	s_add_u32 s2, s2, 0x800
	s_addc_u32 s3, s3, 0
	s_cmp_lg_u32 s87, 0
	s_cselect_b64 s[84:85], s[4:5], s[2:3]
	global_load_dwordx2 v[60:61], v62, s[84:85]
	s_waitcnt vmcnt(31)
	v_add_f32_e32 v66, v66, v67
	v_add_f32_e32 v68, v68, v69
	v_add_f32_e32 v70, v70, v71
	v_add_f32_e32 v72, v72, v73
	v_add_f32_e32 v74, v74, v75
	v_add_f32_e32 v76, v76, v77
	v_add_f32_e32 v78, v78, v79
	v_add_f32_e32 v80, v80, v81
	v_add_f32_e32 v66, v66, v68
	v_add_f32_e32 v70, v70, v72
	v_add_f32_e32 v74, v74, v76
	v_add_f32_e32 v78, v78, v80
	v_add_f32_e32 v66, v66, v70
	v_add_f32_e32 v74, v74, v78
	v_add_f32_e32 v66, v66, v74
	v_fmamk_f32 v66, v66, 0x3a800000, v207
	v_rsq_f32_e32 v66, v66
	s_nop 0
	v_cndmask_b32_e32 v63, 0, v66, vcc
	s_nop 1
	v_readlane_b32 s40, v63, 0
	v_readlane_b32 s41, v63, 1
	v_readlane_b32 s42, v63, 2
	v_readlane_b32 s43, v63, 3
	v_readlane_b32 s44, v63, 4
	v_readlane_b32 s45, v63, 5
	v_readlane_b32 s46, v63, 6
	v_readlane_b32 s47, v63, 7
	v_readlane_b32 s48, v63, 8
	v_readlane_b32 s49, v63, 9
	v_readlane_b32 s50, v63, 10
	v_readlane_b32 s51, v63, 11
	v_readlane_b32 s52, v63, 12
	v_readlane_b32 s53, v63, 13
	v_readlane_b32 s54, v63, 14
	v_readlane_b32 s55, v63, 15
	v_readlane_b32 s56, v63, 16
	v_readlane_b32 s57, v63, 17
	v_readlane_b32 s58, v63, 18
	v_readlane_b32 s59, v63, 19
	v_readlane_b32 s60, v63, 20
	v_readlane_b32 s61, v63, 21
	v_readlane_b32 s62, v63, 22
	v_readlane_b32 s63, v63, 23
	v_readlane_b32 s64, v63, 24
	v_readlane_b32 s65, v63, 25
	v_readlane_b32 s66, v63, 26
	v_readlane_b32 s67, v63, 27
	v_readlane_b32 s68, v63, 28
	v_readlane_b32 s69, v63, 29
	v_readlane_b32 s70, v63, 30
	s_add_u32 s2, s80, 0x9fc8600
	s_addc_u32 s3, s81, 0
	s_lshl_b32 s85, s83, 11
	s_add_u32 s2, s2, s85
	s_addc_u32 s3, s3, 0
	s_waitcnt vmcnt(15)
	v_lshlrev_b32_e32 v86, 16, v0
	v_and_b32_e32 v87, 0xffff0000, v0
	v_lshlrev_b32_e32 v88, 16, v1
	v_and_b32_e32 v89, 0xffff0000, v1
	v_mul_f32_e32 v82, s40, v86
	v_mul_f32_e32 v83, s40, v87
	v_mul_f32_e32 v84, s40, v88
	v_mul_f32_e32 v85, s40, v89
	v_lshlrev_b32_e32 v86, 16, v2
	v_and_b32_e32 v87, 0xffff0000, v2
	v_lshlrev_b32_e32 v88, 16, v3
	v_and_b32_e32 v89, 0xffff0000, v3
	v_fmac_f32_e32 v82, s41, v86
	v_fmac_f32_e32 v83, s41, v87
	v_fmac_f32_e32 v84, s41, v88
	v_fmac_f32_e32 v85, s41, v89
	v_lshlrev_b32_e32 v86, 16, v4
	v_and_b32_e32 v87, 0xffff0000, v4
	v_lshlrev_b32_e32 v88, 16, v5
	v_and_b32_e32 v89, 0xffff0000, v5
	v_fmac_f32_e32 v82, s42, v86
	v_fmac_f32_e32 v83, s42, v87
	v_fmac_f32_e32 v84, s42, v88
	v_fmac_f32_e32 v85, s42, v89
	v_lshlrev_b32_e32 v86, 16, v6
	v_and_b32_e32 v87, 0xffff0000, v6
	v_lshlrev_b32_e32 v88, 16, v7
	v_and_b32_e32 v89, 0xffff0000, v7
	v_fmac_f32_e32 v82, s43, v86
	v_fmac_f32_e32 v83, s43, v87
	v_fmac_f32_e32 v84, s43, v88
	v_fmac_f32_e32 v85, s43, v89
	v_lshlrev_b32_e32 v86, 16, v8
	v_and_b32_e32 v87, 0xffff0000, v8
	v_lshlrev_b32_e32 v88, 16, v9
	v_and_b32_e32 v89, 0xffff0000, v9
	v_fmac_f32_e32 v82, s44, v86
	v_fmac_f32_e32 v83, s44, v87
	v_fmac_f32_e32 v84, s44, v88
	v_fmac_f32_e32 v85, s44, v89
	v_lshlrev_b32_e32 v86, 16, v10
	v_and_b32_e32 v87, 0xffff0000, v10
	v_lshlrev_b32_e32 v88, 16, v11
	v_and_b32_e32 v89, 0xffff0000, v11
	v_fmac_f32_e32 v82, s45, v86
	v_fmac_f32_e32 v83, s45, v87
	v_fmac_f32_e32 v84, s45, v88
	v_fmac_f32_e32 v85, s45, v89
	v_lshlrev_b32_e32 v86, 16, v12
	v_and_b32_e32 v87, 0xffff0000, v12
	v_lshlrev_b32_e32 v88, 16, v13
	v_and_b32_e32 v89, 0xffff0000, v13
	v_fmac_f32_e32 v82, s46, v86
	v_fmac_f32_e32 v83, s46, v87
	v_fmac_f32_e32 v84, s46, v88
	v_fmac_f32_e32 v85, s46, v89
	v_lshlrev_b32_e32 v86, 16, v14
	v_and_b32_e32 v87, 0xffff0000, v14
	v_lshlrev_b32_e32 v88, 16, v15
	v_and_b32_e32 v89, 0xffff0000, v15
	v_fmac_f32_e32 v82, s47, v86
	v_fmac_f32_e32 v83, s47, v87
	v_fmac_f32_e32 v84, s47, v88
	v_fmac_f32_e32 v85, s47, v89
	v_lshlrev_b32_e32 v86, 16, v16
	v_and_b32_e32 v87, 0xffff0000, v16
	v_lshlrev_b32_e32 v88, 16, v17
	v_and_b32_e32 v89, 0xffff0000, v17
	v_fmac_f32_e32 v82, s48, v86
	v_fmac_f32_e32 v83, s48, v87
	v_fmac_f32_e32 v84, s48, v88
	v_fmac_f32_e32 v85, s48, v89
	v_lshlrev_b32_e32 v86, 16, v18
	v_and_b32_e32 v87, 0xffff0000, v18
	v_lshlrev_b32_e32 v88, 16, v19
	v_and_b32_e32 v89, 0xffff0000, v19
	v_fmac_f32_e32 v82, s49, v86
	v_fmac_f32_e32 v83, s49, v87
	v_fmac_f32_e32 v84, s49, v88
	v_fmac_f32_e32 v85, s49, v89
	v_lshlrev_b32_e32 v86, 16, v20
	v_and_b32_e32 v87, 0xffff0000, v20
	v_lshlrev_b32_e32 v88, 16, v21
	v_and_b32_e32 v89, 0xffff0000, v21
	v_fmac_f32_e32 v82, s50, v86
	v_fmac_f32_e32 v83, s50, v87
	v_fmac_f32_e32 v84, s50, v88
	v_fmac_f32_e32 v85, s50, v89
	v_lshlrev_b32_e32 v86, 16, v22
	v_and_b32_e32 v87, 0xffff0000, v22
	v_lshlrev_b32_e32 v88, 16, v23
	v_and_b32_e32 v89, 0xffff0000, v23
	v_fmac_f32_e32 v82, s51, v86
	v_fmac_f32_e32 v83, s51, v87
	v_fmac_f32_e32 v84, s51, v88
	v_fmac_f32_e32 v85, s51, v89
	v_lshlrev_b32_e32 v86, 16, v24
	v_and_b32_e32 v87, 0xffff0000, v24
	v_lshlrev_b32_e32 v88, 16, v25
	v_and_b32_e32 v89, 0xffff0000, v25
	v_fmac_f32_e32 v82, s52, v86
	v_fmac_f32_e32 v83, s52, v87
	v_fmac_f32_e32 v84, s52, v88
	v_fmac_f32_e32 v85, s52, v89
	v_lshlrev_b32_e32 v86, 16, v26
	v_and_b32_e32 v87, 0xffff0000, v26
	v_lshlrev_b32_e32 v88, 16, v27
	v_and_b32_e32 v89, 0xffff0000, v27
	v_fmac_f32_e32 v82, s53, v86
	v_fmac_f32_e32 v83, s53, v87
	v_fmac_f32_e32 v84, s53, v88
	v_fmac_f32_e32 v85, s53, v89
	v_lshlrev_b32_e32 v86, 16, v28
	v_and_b32_e32 v87, 0xffff0000, v28
	v_lshlrev_b32_e32 v88, 16, v29
	v_and_b32_e32 v89, 0xffff0000, v29
	v_fmac_f32_e32 v82, s54, v86
	v_fmac_f32_e32 v83, s54, v87
	v_fmac_f32_e32 v84, s54, v88
	v_fmac_f32_e32 v85, s54, v89
	v_lshlrev_b32_e32 v86, 16, v30
	v_and_b32_e32 v87, 0xffff0000, v30
	v_lshlrev_b32_e32 v88, 16, v31
	v_and_b32_e32 v89, 0xffff0000, v31
	v_fmac_f32_e32 v82, s55, v86
	v_fmac_f32_e32 v83, s55, v87
	v_fmac_f32_e32 v84, s55, v88
	v_fmac_f32_e32 v85, s55, v89
	s_cmp_lg_u32 s86, 0
	s_mov_b32 s84, 0x3d800000
	s_cselect_b32 s84, 0x3e000000, s84
	v_lshlrev_b32_e32 v86, 16, v16
	v_and_b32_e32 v87, 0xffff0000, v16
	v_lshlrev_b32_e32 v88, 16, v17
	v_and_b32_e32 v89, 0xffff0000, v17
	v_mul_f32_e32 v86, s48, v86
	v_mul_f32_e32 v87, s48, v87
	v_mul_f32_e32 v88, s48, v88
	v_mul_f32_e32 v89, s48, v89
	v_fma_f32 v90, v82, s84, -v86
	v_fma_f32 v91, v83, s84, -v87
	v_fma_f32 v92, v84, s84, -v88
	v_fma_f32 v93, v85, s84, -v89
	v_cvt_pk_bf16_f32 v94, v90, v91
	v_cvt_pk_bf16_f32 v95, v92, v93
	global_store_dwordx2 v62, v[94:95], s[2:3]
	s_add_u32 s2, s2, 0x800
	s_addc_u32 s3, s3, 0
	s_waitcnt vmcnt(15)
	v_lshlrev_b32_e32 v86, 16, v32
	v_and_b32_e32 v87, 0xffff0000, v32
	v_lshlrev_b32_e32 v88, 16, v33
	v_and_b32_e32 v89, 0xffff0000, v33
	v_fmac_f32_e32 v82, s56, v86
	v_fmac_f32_e32 v83, s56, v87
	v_fmac_f32_e32 v84, s56, v88
	v_fmac_f32_e32 v85, s56, v89
	v_lshlrev_b32_e32 v86, 16, v0
	v_and_b32_e32 v87, 0xffff0000, v0
	v_lshlrev_b32_e32 v88, 16, v1
	v_and_b32_e32 v89, 0xffff0000, v1
	v_fma_f32 v82, -v86, s40, v82
	v_fma_f32 v83, -v87, s40, v83
	v_fma_f32 v84, -v88, s40, v84
	v_fma_f32 v85, -v89, s40, v85
	s_cmp_lg_u32 s86, 0
	s_mov_b32 s84, 0x3d800000
	s_cselect_b32 s84, 0x3de38e39, s84
	v_lshlrev_b32_e32 v86, 16, v18
	v_and_b32_e32 v87, 0xffff0000, v18
	v_lshlrev_b32_e32 v88, 16, v19
	v_and_b32_e32 v89, 0xffff0000, v19
	v_mul_f32_e32 v86, s49, v86
	v_mul_f32_e32 v87, s49, v87
	v_mul_f32_e32 v88, s49, v88
	v_mul_f32_e32 v89, s49, v89
	v_fma_f32 v90, v82, s84, -v86
	v_fma_f32 v91, v83, s84, -v87
	v_fma_f32 v92, v84, s84, -v88
	v_fma_f32 v93, v85, s84, -v89
	v_cvt_pk_bf16_f32 v94, v90, v91
	v_cvt_pk_bf16_f32 v95, v92, v93
	global_store_dwordx2 v62, v[94:95], s[2:3]
	s_add_u32 s2, s2, 0x800
	s_addc_u32 s3, s3, 0
	s_waitcnt vmcnt(15)
	v_lshlrev_b32_e32 v86, 16, v34
	v_and_b32_e32 v87, 0xffff0000, v34
	v_lshlrev_b32_e32 v88, 16, v35
	v_and_b32_e32 v89, 0xffff0000, v35
	v_fmac_f32_e32 v82, s57, v86
	v_fmac_f32_e32 v83, s57, v87
	v_fmac_f32_e32 v84, s57, v88
	v_fmac_f32_e32 v85, s57, v89
	v_lshlrev_b32_e32 v86, 16, v2
	v_and_b32_e32 v87, 0xffff0000, v2
	v_lshlrev_b32_e32 v88, 16, v3
	v_and_b32_e32 v89, 0xffff0000, v3
	v_fma_f32 v82, -v86, s41, v82
	v_fma_f32 v83, -v87, s41, v83
	v_fma_f32 v84, -v88, s41, v84
	v_fma_f32 v85, -v89, s41, v85
	s_cmp_lg_u32 s86, 0
	s_mov_b32 s84, 0x3d800000
	s_cselect_b32 s84, 0x3dcccccd, s84
	v_lshlrev_b32_e32 v86, 16, v20
	v_and_b32_e32 v87, 0xffff0000, v20
	v_lshlrev_b32_e32 v88, 16, v21
	v_and_b32_e32 v89, 0xffff0000, v21
	v_mul_f32_e32 v86, s50, v86
	v_mul_f32_e32 v87, s50, v87
	v_mul_f32_e32 v88, s50, v88
	v_mul_f32_e32 v89, s50, v89
	v_fma_f32 v90, v82, s84, -v86
	v_fma_f32 v91, v83, s84, -v87
	v_fma_f32 v92, v84, s84, -v88
	v_fma_f32 v93, v85, s84, -v89
	v_cvt_pk_bf16_f32 v94, v90, v91
	v_cvt_pk_bf16_f32 v95, v92, v93
	global_store_dwordx2 v62, v[94:95], s[2:3]
	s_add_u32 s2, s2, 0x800
	s_addc_u32 s3, s3, 0
	s_waitcnt vmcnt(15)
	v_lshlrev_b32_e32 v86, 16, v36
	v_and_b32_e32 v87, 0xffff0000, v36
	v_lshlrev_b32_e32 v88, 16, v37
	v_and_b32_e32 v89, 0xffff0000, v37
	v_fmac_f32_e32 v82, s58, v86
	v_fmac_f32_e32 v83, s58, v87
	v_fmac_f32_e32 v84, s58, v88
	v_fmac_f32_e32 v85, s58, v89
	v_lshlrev_b32_e32 v86, 16, v4
	v_and_b32_e32 v87, 0xffff0000, v4
	v_lshlrev_b32_e32 v88, 16, v5
	v_and_b32_e32 v89, 0xffff0000, v5
	v_fma_f32 v82, -v86, s42, v82
	v_fma_f32 v83, -v87, s42, v83
	v_fma_f32 v84, -v88, s42, v84
	v_fma_f32 v85, -v89, s42, v85
	s_cmp_lg_u32 s86, 0
	s_mov_b32 s84, 0x3d800000
	s_cselect_b32 s84, 0x3dba2e8c, s84
	v_lshlrev_b32_e32 v86, 16, v22
	v_and_b32_e32 v87, 0xffff0000, v22
	v_lshlrev_b32_e32 v88, 16, v23
	v_and_b32_e32 v89, 0xffff0000, v23
	v_mul_f32_e32 v86, s51, v86
	v_mul_f32_e32 v87, s51, v87
	v_mul_f32_e32 v88, s51, v88
	v_mul_f32_e32 v89, s51, v89
	v_fma_f32 v90, v82, s84, -v86
	v_fma_f32 v91, v83, s84, -v87
	v_fma_f32 v92, v84, s84, -v88
	v_fma_f32 v93, v85, s84, -v89
	v_cvt_pk_bf16_f32 v94, v90, v91
	v_cvt_pk_bf16_f32 v95, v92, v93
	global_store_dwordx2 v62, v[94:95], s[2:3]
	s_add_u32 s2, s2, 0x800
	s_addc_u32 s3, s3, 0
	s_waitcnt vmcnt(15)
	v_lshlrev_b32_e32 v86, 16, v38
	v_and_b32_e32 v87, 0xffff0000, v38
	v_lshlrev_b32_e32 v88, 16, v39
	v_and_b32_e32 v89, 0xffff0000, v39
	v_fmac_f32_e32 v82, s59, v86
	v_fmac_f32_e32 v83, s59, v87
	v_fmac_f32_e32 v84, s59, v88
	v_fmac_f32_e32 v85, s59, v89
	v_lshlrev_b32_e32 v86, 16, v6
	v_and_b32_e32 v87, 0xffff0000, v6
	v_lshlrev_b32_e32 v88, 16, v7
	v_and_b32_e32 v89, 0xffff0000, v7
	v_fma_f32 v82, -v86, s43, v82
	v_fma_f32 v83, -v87, s43, v83
	v_fma_f32 v84, -v88, s43, v84
	v_fma_f32 v85, -v89, s43, v85
	s_cmp_lg_u32 s86, 0
	s_mov_b32 s84, 0x3d800000
	s_cselect_b32 s84, 0x3daaaaab, s84
	v_lshlrev_b32_e32 v86, 16, v24
	v_and_b32_e32 v87, 0xffff0000, v24
	v_lshlrev_b32_e32 v88, 16, v25
	v_and_b32_e32 v89, 0xffff0000, v25
	v_mul_f32_e32 v86, s52, v86
	v_mul_f32_e32 v87, s52, v87
	v_mul_f32_e32 v88, s52, v88
	v_mul_f32_e32 v89, s52, v89
	v_fma_f32 v90, v82, s84, -v86
	v_fma_f32 v91, v83, s84, -v87
	v_fma_f32 v92, v84, s84, -v88
	v_fma_f32 v93, v85, s84, -v89
	v_cvt_pk_bf16_f32 v94, v90, v91
	v_cvt_pk_bf16_f32 v95, v92, v93
	global_store_dwordx2 v62, v[94:95], s[2:3]
	s_add_u32 s2, s2, 0x800
	s_addc_u32 s3, s3, 0
	s_waitcnt vmcnt(15)
	v_lshlrev_b32_e32 v86, 16, v40
	v_and_b32_e32 v87, 0xffff0000, v40
	v_lshlrev_b32_e32 v88, 16, v41
	v_and_b32_e32 v89, 0xffff0000, v41
	v_fmac_f32_e32 v82, s60, v86
	v_fmac_f32_e32 v83, s60, v87
	v_fmac_f32_e32 v84, s60, v88
	v_fmac_f32_e32 v85, s60, v89
	v_lshlrev_b32_e32 v86, 16, v8
	v_and_b32_e32 v87, 0xffff0000, v8
	v_lshlrev_b32_e32 v88, 16, v9
	v_and_b32_e32 v89, 0xffff0000, v9
	v_fma_f32 v82, -v86, s44, v82
	v_fma_f32 v83, -v87, s44, v83
	v_fma_f32 v84, -v88, s44, v84
	v_fma_f32 v85, -v89, s44, v85
	s_cmp_lg_u32 s86, 0
	s_mov_b32 s84, 0x3d800000
	s_cselect_b32 s84, 0x3d9d89d9, s84
	v_lshlrev_b32_e32 v86, 16, v26
	v_and_b32_e32 v87, 0xffff0000, v26
	v_lshlrev_b32_e32 v88, 16, v27
	v_and_b32_e32 v89, 0xffff0000, v27
	v_mul_f32_e32 v86, s53, v86
	v_mul_f32_e32 v87, s53, v87
	v_mul_f32_e32 v88, s53, v88
	v_mul_f32_e32 v89, s53, v89
	v_fma_f32 v90, v82, s84, -v86
	v_fma_f32 v91, v83, s84, -v87
	v_fma_f32 v92, v84, s84, -v88
	v_fma_f32 v93, v85, s84, -v89
	v_cvt_pk_bf16_f32 v94, v90, v91
	v_cvt_pk_bf16_f32 v95, v92, v93
	global_store_dwordx2 v62, v[94:95], s[2:3]
	s_add_u32 s2, s2, 0x800
	s_addc_u32 s3, s3, 0
	s_waitcnt vmcnt(15)
	v_lshlrev_b32_e32 v86, 16, v42
	v_and_b32_e32 v87, 0xffff0000, v42
	v_lshlrev_b32_e32 v88, 16, v43
	v_and_b32_e32 v89, 0xffff0000, v43
	v_fmac_f32_e32 v82, s61, v86
	v_fmac_f32_e32 v83, s61, v87
	v_fmac_f32_e32 v84, s61, v88
	v_fmac_f32_e32 v85, s61, v89
	v_lshlrev_b32_e32 v86, 16, v10
	v_and_b32_e32 v87, 0xffff0000, v10
	v_lshlrev_b32_e32 v88, 16, v11
	v_and_b32_e32 v89, 0xffff0000, v11
	v_fma_f32 v82, -v86, s45, v82
	v_fma_f32 v83, -v87, s45, v83
	v_fma_f32 v84, -v88, s45, v84
	v_fma_f32 v85, -v89, s45, v85
	s_cmp_lg_u32 s86, 0
	s_mov_b32 s84, 0x3d800000
	s_cselect_b32 s84, 0x3d924925, s84
	v_lshlrev_b32_e32 v86, 16, v28
	v_and_b32_e32 v87, 0xffff0000, v28
	v_lshlrev_b32_e32 v88, 16, v29
	v_and_b32_e32 v89, 0xffff0000, v29
	v_mul_f32_e32 v86, s54, v86
	v_mul_f32_e32 v87, s54, v87
	v_mul_f32_e32 v88, s54, v88
	v_mul_f32_e32 v89, s54, v89
	v_fma_f32 v90, v82, s84, -v86
	v_fma_f32 v91, v83, s84, -v87
	v_fma_f32 v92, v84, s84, -v88
	v_fma_f32 v93, v85, s84, -v89
	v_cvt_pk_bf16_f32 v94, v90, v91
	v_cvt_pk_bf16_f32 v95, v92, v93
	global_store_dwordx2 v62, v[94:95], s[2:3]
	s_add_u32 s2, s2, 0x800
	s_addc_u32 s3, s3, 0
	s_waitcnt vmcnt(15)
	v_lshlrev_b32_e32 v86, 16, v44
	v_and_b32_e32 v87, 0xffff0000, v44
	v_lshlrev_b32_e32 v88, 16, v45
	v_and_b32_e32 v89, 0xffff0000, v45
	v_fmac_f32_e32 v82, s62, v86
	v_fmac_f32_e32 v83, s62, v87
	v_fmac_f32_e32 v84, s62, v88
	v_fmac_f32_e32 v85, s62, v89
	v_lshlrev_b32_e32 v86, 16, v12
	v_and_b32_e32 v87, 0xffff0000, v12
	v_lshlrev_b32_e32 v88, 16, v13
	v_and_b32_e32 v89, 0xffff0000, v13
	v_fma_f32 v82, -v86, s46, v82
	v_fma_f32 v83, -v87, s46, v83
	v_fma_f32 v84, -v88, s46, v84
	v_fma_f32 v85, -v89, s46, v85
	s_cmp_lg_u32 s86, 0
	s_mov_b32 s84, 0x3d800000
	s_cselect_b32 s84, 0x3d888889, s84
	v_lshlrev_b32_e32 v86, 16, v30
	v_and_b32_e32 v87, 0xffff0000, v30
	v_lshlrev_b32_e32 v88, 16, v31
	v_and_b32_e32 v89, 0xffff0000, v31
	v_mul_f32_e32 v86, s55, v86
	v_mul_f32_e32 v87, s55, v87
	v_mul_f32_e32 v88, s55, v88
	v_mul_f32_e32 v89, s55, v89
	v_fma_f32 v90, v82, s84, -v86
	v_fma_f32 v91, v83, s84, -v87
	v_fma_f32 v92, v84, s84, -v88
	v_fma_f32 v93, v85, s84, -v89
	v_cvt_pk_bf16_f32 v94, v90, v91
	v_cvt_pk_bf16_f32 v95, v92, v93
	global_store_dwordx2 v62, v[94:95], s[2:3]
	s_add_u32 s2, s2, 0x800
	s_addc_u32 s3, s3, 0
	s_waitcnt vmcnt(15)
	v_lshlrev_b32_e32 v86, 16, v46
	v_and_b32_e32 v87, 0xffff0000, v46
	v_lshlrev_b32_e32 v88, 16, v47
	v_and_b32_e32 v89, 0xffff0000, v47
	v_fmac_f32_e32 v82, s63, v86
	v_fmac_f32_e32 v83, s63, v87
	v_fmac_f32_e32 v84, s63, v88
	v_fmac_f32_e32 v85, s63, v89
	v_lshlrev_b32_e32 v86, 16, v14
	v_and_b32_e32 v87, 0xffff0000, v14
	v_lshlrev_b32_e32 v88, 16, v15
	v_and_b32_e32 v89, 0xffff0000, v15
	v_fma_f32 v82, -v86, s47, v82
	v_fma_f32 v83, -v87, s47, v83
	v_fma_f32 v84, -v88, s47, v84
	v_fma_f32 v85, -v89, s47, v85
	s_mov_b32 s84, 0x3d800000
	v_lshlrev_b32_e32 v86, 16, v32
	v_and_b32_e32 v87, 0xffff0000, v32
	v_lshlrev_b32_e32 v88, 16, v33
	v_and_b32_e32 v89, 0xffff0000, v33
	v_mul_f32_e32 v86, s56, v86
	v_mul_f32_e32 v87, s56, v87
	v_mul_f32_e32 v88, s56, v88
	v_mul_f32_e32 v89, s56, v89
	v_fma_f32 v90, v82, s84, -v86
	v_fma_f32 v91, v83, s84, -v87
	v_fma_f32 v92, v84, s84, -v88
	v_fma_f32 v93, v85, s84, -v89
	v_cvt_pk_bf16_f32 v94, v90, v91
	v_cvt_pk_bf16_f32 v95, v92, v93
	global_store_dwordx2 v62, v[94:95], s[2:3]
	s_add_u32 s2, s2, 0x800
	s_addc_u32 s3, s3, 0
	s_waitcnt vmcnt(15)
	v_lshlrev_b32_e32 v86, 16, v48
	v_and_b32_e32 v87, 0xffff0000, v48
	v_lshlrev_b32_e32 v88, 16, v49
	v_and_b32_e32 v89, 0xffff0000, v49
	v_fmac_f32_e32 v82, s64, v86
	v_fmac_f32_e32 v83, s64, v87
	v_fmac_f32_e32 v84, s64, v88
	v_fmac_f32_e32 v85, s64, v89
	v_lshlrev_b32_e32 v86, 16, v16
	v_and_b32_e32 v87, 0xffff0000, v16
	v_lshlrev_b32_e32 v88, 16, v17
	v_and_b32_e32 v89, 0xffff0000, v17
	v_fma_f32 v82, -v86, s48, v82
	v_fma_f32 v83, -v87, s48, v83
	v_fma_f32 v84, -v88, s48, v84
	v_fma_f32 v85, -v89, s48, v85
	s_cmp_lg_u32 s87, 0
	s_mov_b32 s84, 0x3d800000
	s_cselect_b32 s84, 0x3d888889, s84
	v_lshlrev_b32_e32 v86, 16, v34
	v_and_b32_e32 v87, 0xffff0000, v34
	v_lshlrev_b32_e32 v88, 16, v35
	v_and_b32_e32 v89, 0xffff0000, v35
	v_mul_f32_e32 v86, s57, v86
	v_mul_f32_e32 v87, s57, v87
	v_mul_f32_e32 v88, s57, v88
	v_mul_f32_e32 v89, s57, v89
	v_fma_f32 v90, v82, s84, -v86
	v_fma_f32 v91, v83, s84, -v87
	v_fma_f32 v92, v84, s84, -v88
	v_fma_f32 v93, v85, s84, -v89
	v_cvt_pk_bf16_f32 v94, v90, v91
	v_cvt_pk_bf16_f32 v95, v92, v93
	global_store_dwordx2 v62, v[94:95], s[2:3]
	s_add_u32 s2, s2, 0x800
	s_addc_u32 s3, s3, 0
	s_waitcnt vmcnt(15)
	v_lshlrev_b32_e32 v86, 16, v50
	v_and_b32_e32 v87, 0xffff0000, v50
	v_lshlrev_b32_e32 v88, 16, v51
	v_and_b32_e32 v89, 0xffff0000, v51
	v_fmac_f32_e32 v82, s65, v86
	v_fmac_f32_e32 v83, s65, v87
	v_fmac_f32_e32 v84, s65, v88
	v_fmac_f32_e32 v85, s65, v89
	v_lshlrev_b32_e32 v86, 16, v18
	v_and_b32_e32 v87, 0xffff0000, v18
	v_lshlrev_b32_e32 v88, 16, v19
	v_and_b32_e32 v89, 0xffff0000, v19
	v_fma_f32 v82, -v86, s49, v82
	v_fma_f32 v83, -v87, s49, v83
	v_fma_f32 v84, -v88, s49, v84
	v_fma_f32 v85, -v89, s49, v85
	s_cmp_lg_u32 s87, 0
	s_mov_b32 s84, 0x3d800000
	s_cselect_b32 s84, 0x3d924925, s84
	v_lshlrev_b32_e32 v86, 16, v36
	v_and_b32_e32 v87, 0xffff0000, v36
	v_lshlrev_b32_e32 v88, 16, v37
	v_and_b32_e32 v89, 0xffff0000, v37
	v_mul_f32_e32 v86, s58, v86
	v_mul_f32_e32 v87, s58, v87
	v_mul_f32_e32 v88, s58, v88
	v_mul_f32_e32 v89, s58, v89
	v_fma_f32 v90, v82, s84, -v86
	v_fma_f32 v91, v83, s84, -v87
	v_fma_f32 v92, v84, s84, -v88
	v_fma_f32 v93, v85, s84, -v89
	v_cvt_pk_bf16_f32 v94, v90, v91
	v_cvt_pk_bf16_f32 v95, v92, v93
	global_store_dwordx2 v62, v[94:95], s[2:3]
	s_add_u32 s2, s2, 0x800
	s_addc_u32 s3, s3, 0
	s_waitcnt vmcnt(15)
	v_lshlrev_b32_e32 v86, 16, v52
	v_and_b32_e32 v87, 0xffff0000, v52
	v_lshlrev_b32_e32 v88, 16, v53
	v_and_b32_e32 v89, 0xffff0000, v53
	v_fmac_f32_e32 v82, s66, v86
	v_fmac_f32_e32 v83, s66, v87
	v_fmac_f32_e32 v84, s66, v88
	v_fmac_f32_e32 v85, s66, v89
	v_lshlrev_b32_e32 v86, 16, v20
	v_and_b32_e32 v87, 0xffff0000, v20
	v_lshlrev_b32_e32 v88, 16, v21
	v_and_b32_e32 v89, 0xffff0000, v21
	v_fma_f32 v82, -v86, s50, v82
	v_fma_f32 v83, -v87, s50, v83
	v_fma_f32 v84, -v88, s50, v84
	v_fma_f32 v85, -v89, s50, v85
	s_cmp_lg_u32 s87, 0
	s_mov_b32 s84, 0x3d800000
	s_cselect_b32 s84, 0x3d9d89d9, s84
	v_lshlrev_b32_e32 v86, 16, v38
	v_and_b32_e32 v87, 0xffff0000, v38
	v_lshlrev_b32_e32 v88, 16, v39
	v_and_b32_e32 v89, 0xffff0000, v39
	v_mul_f32_e32 v86, s59, v86
	v_mul_f32_e32 v87, s59, v87
	v_mul_f32_e32 v88, s59, v88
	v_mul_f32_e32 v89, s59, v89
	v_fma_f32 v90, v82, s84, -v86
	v_fma_f32 v91, v83, s84, -v87
	v_fma_f32 v92, v84, s84, -v88
	v_fma_f32 v93, v85, s84, -v89
	v_cvt_pk_bf16_f32 v94, v90, v91
	v_cvt_pk_bf16_f32 v95, v92, v93
	global_store_dwordx2 v62, v[94:95], s[2:3]
	s_add_u32 s2, s2, 0x800
	s_addc_u32 s3, s3, 0
	s_waitcnt vmcnt(15)
	v_lshlrev_b32_e32 v86, 16, v54
	v_and_b32_e32 v87, 0xffff0000, v54
	v_lshlrev_b32_e32 v88, 16, v55
	v_and_b32_e32 v89, 0xffff0000, v55
	v_fmac_f32_e32 v82, s67, v86
	v_fmac_f32_e32 v83, s67, v87
	v_fmac_f32_e32 v84, s67, v88
	v_fmac_f32_e32 v85, s67, v89
	v_lshlrev_b32_e32 v86, 16, v22
	v_and_b32_e32 v87, 0xffff0000, v22
	v_lshlrev_b32_e32 v88, 16, v23
	v_and_b32_e32 v89, 0xffff0000, v23
	v_fma_f32 v82, -v86, s51, v82
	v_fma_f32 v83, -v87, s51, v83
	v_fma_f32 v84, -v88, s51, v84
	v_fma_f32 v85, -v89, s51, v85
	s_cmp_lg_u32 s87, 0
	s_mov_b32 s84, 0x3d800000
	s_cselect_b32 s84, 0x3daaaaab, s84
	v_lshlrev_b32_e32 v86, 16, v40
	v_and_b32_e32 v87, 0xffff0000, v40
	v_lshlrev_b32_e32 v88, 16, v41
	v_and_b32_e32 v89, 0xffff0000, v41
	v_mul_f32_e32 v86, s60, v86
	v_mul_f32_e32 v87, s60, v87
	v_mul_f32_e32 v88, s60, v88
	v_mul_f32_e32 v89, s60, v89
	v_fma_f32 v90, v82, s84, -v86
	v_fma_f32 v91, v83, s84, -v87
	v_fma_f32 v92, v84, s84, -v88
	v_fma_f32 v93, v85, s84, -v89
	v_cvt_pk_bf16_f32 v94, v90, v91
	v_cvt_pk_bf16_f32 v95, v92, v93
	global_store_dwordx2 v62, v[94:95], s[2:3]
	s_add_u32 s2, s2, 0x800
	s_addc_u32 s3, s3, 0
	s_waitcnt vmcnt(15)
	v_lshlrev_b32_e32 v86, 16, v56
	v_and_b32_e32 v87, 0xffff0000, v56
	v_lshlrev_b32_e32 v88, 16, v57
	v_and_b32_e32 v89, 0xffff0000, v57
	v_fmac_f32_e32 v82, s68, v86
	v_fmac_f32_e32 v83, s68, v87
	v_fmac_f32_e32 v84, s68, v88
	v_fmac_f32_e32 v85, s68, v89
	v_lshlrev_b32_e32 v86, 16, v24
	v_and_b32_e32 v87, 0xffff0000, v24
	v_lshlrev_b32_e32 v88, 16, v25
	v_and_b32_e32 v89, 0xffff0000, v25
	v_fma_f32 v82, -v86, s52, v82
	v_fma_f32 v83, -v87, s52, v83
	v_fma_f32 v84, -v88, s52, v84
	v_fma_f32 v85, -v89, s52, v85
	s_cmp_lg_u32 s87, 0
	s_mov_b32 s84, 0x3d800000
	s_cselect_b32 s84, 0x3dba2e8c, s84
	v_lshlrev_b32_e32 v86, 16, v42
	v_and_b32_e32 v87, 0xffff0000, v42
	v_lshlrev_b32_e32 v88, 16, v43
	v_and_b32_e32 v89, 0xffff0000, v43
	v_mul_f32_e32 v86, s61, v86
	v_mul_f32_e32 v87, s61, v87
	v_mul_f32_e32 v88, s61, v88
	v_mul_f32_e32 v89, s61, v89
	v_fma_f32 v90, v82, s84, -v86
	v_fma_f32 v91, v83, s84, -v87
	v_fma_f32 v92, v84, s84, -v88
	v_fma_f32 v93, v85, s84, -v89
	v_cvt_pk_bf16_f32 v94, v90, v91
	v_cvt_pk_bf16_f32 v95, v92, v93
	global_store_dwordx2 v62, v[94:95], s[2:3]
	s_add_u32 s2, s2, 0x800
	s_addc_u32 s3, s3, 0
	s_waitcnt vmcnt(15)
	v_lshlrev_b32_e32 v86, 16, v58
	v_and_b32_e32 v87, 0xffff0000, v58
	v_lshlrev_b32_e32 v88, 16, v59
	v_and_b32_e32 v89, 0xffff0000, v59
	v_fmac_f32_e32 v82, s69, v86
	v_fmac_f32_e32 v83, s69, v87
	v_fmac_f32_e32 v84, s69, v88
	v_fmac_f32_e32 v85, s69, v89
	v_lshlrev_b32_e32 v86, 16, v26
	v_and_b32_e32 v87, 0xffff0000, v26
	v_lshlrev_b32_e32 v88, 16, v27
	v_and_b32_e32 v89, 0xffff0000, v27
	v_fma_f32 v82, -v86, s53, v82
	v_fma_f32 v83, -v87, s53, v83
	v_fma_f32 v84, -v88, s53, v84
	v_fma_f32 v85, -v89, s53, v85
	s_cmp_lg_u32 s87, 0
	s_mov_b32 s84, 0x3d800000
	s_cselect_b32 s84, 0x3dcccccd, s84
	v_lshlrev_b32_e32 v86, 16, v44
	v_and_b32_e32 v87, 0xffff0000, v44
	v_lshlrev_b32_e32 v88, 16, v45
	v_and_b32_e32 v89, 0xffff0000, v45
	v_mul_f32_e32 v86, s62, v86
	v_mul_f32_e32 v87, s62, v87
	v_mul_f32_e32 v88, s62, v88
	v_mul_f32_e32 v89, s62, v89
	v_fma_f32 v90, v82, s84, -v86
	v_fma_f32 v91, v83, s84, -v87
	v_fma_f32 v92, v84, s84, -v88
	v_fma_f32 v93, v85, s84, -v89
	v_cvt_pk_bf16_f32 v94, v90, v91
	v_cvt_pk_bf16_f32 v95, v92, v93
	global_store_dwordx2 v62, v[94:95], s[2:3]
	s_add_u32 s2, s2, 0x800
	s_addc_u32 s3, s3, 0
	s_waitcnt vmcnt(15)
	v_lshlrev_b32_e32 v86, 16, v60
	v_and_b32_e32 v87, 0xffff0000, v60
	v_lshlrev_b32_e32 v88, 16, v61
	v_and_b32_e32 v89, 0xffff0000, v61
	v_fmac_f32_e32 v82, s70, v86
	v_fmac_f32_e32 v83, s70, v87
	v_fmac_f32_e32 v84, s70, v88
	v_fmac_f32_e32 v85, s70, v89
	v_lshlrev_b32_e32 v86, 16, v28
	v_and_b32_e32 v87, 0xffff0000, v28
	v_lshlrev_b32_e32 v88, 16, v29
	v_and_b32_e32 v89, 0xffff0000, v29
	v_fma_f32 v82, -v86, s54, v82
	v_fma_f32 v83, -v87, s54, v83
	v_fma_f32 v84, -v88, s54, v84
	v_fma_f32 v85, -v89, s54, v85
	s_cmp_lg_u32 s87, 0
	s_mov_b32 s84, 0x3d800000
	s_cselect_b32 s84, 0x3de38e39, s84
	v_lshlrev_b32_e32 v86, 16, v46
	v_and_b32_e32 v87, 0xffff0000, v46
	v_lshlrev_b32_e32 v88, 16, v47
	v_and_b32_e32 v89, 0xffff0000, v47
	v_mul_f32_e32 v86, s63, v86
	v_mul_f32_e32 v87, s63, v87
	v_mul_f32_e32 v88, s63, v88
	v_mul_f32_e32 v89, s63, v89
	v_fma_f32 v90, v82, s84, -v86
	v_fma_f32 v91, v83, s84, -v87
	v_fma_f32 v92, v84, s84, -v88
	v_fma_f32 v93, v85, s84, -v89
	v_cvt_pk_bf16_f32 v94, v90, v91
	v_cvt_pk_bf16_f32 v95, v92, v93
	global_store_dwordx2 v62, v[94:95], s[2:3]
	s_branch .Lpool_next
.Lpool_next:
	s_add_i32 s71, s71, 64
	s_cmpk_lt_u32 s71, 0x60
	s_cbranch_scc1 .Lpool_task

.LBB0_961:
	s_andn2_saveexec_b64 s[2:3], s[42:43]
	s_cbranch_execz .LBB0_979
	s_mov_b64 s[42:43], exec
	s_cmp_eq_u32 s36, 7
	s_cbranch_scc1 .Lxl_fout_chk
	s_cmp_lg_u32 s36, 2
	s_cbranch_scc1 .Lxl_fout_no
.Lxl_fout_chk:
	v_mov_b32_e32 v1, 0x20810
	ds_read_b32 v1, v1
	s_waitcnt lgkmcnt(0)
	v_readfirstlane_b32 s2, v1
	s_cmp_lg_u32 s2, 0
	s_cbranch_scc1 .Lxl_fout_skip
